# one static s_setprio 1 for waves 4-7 inside the hand-written window, retention-intra and banded attention regions (reset to 0 at their exits)
# speedup vs baseline: 1.0049x; 1.0049x over previous
.LBB0_399:
	s_or_b64 exec, exec, s[12:13]
	v_mov_b32_e32 v2, v208
	s_add_u32 s30, s26, 0x6d00000
	s_addc_u32 s31, s27, 0
	v_and_b32_e32 v102, 15, v2
	v_lshlrev_b32_e32 v84, 6, v102
	v_mov_b32_e32 v85, v65
	s_add_u32 s34, s26, 0x1ad00000
	v_lshl_add_u64 v[0:1], s[26:27], 0, v[84:85]
	v_and_b32_e32 v86, 48, v2
	v_mov_b32_e32 v87, v65
	v_and_b32_e32 v3, 63, v2
	s_addc_u32 s35, s27, 0
	v_lshl_add_u64 v[0:1], v[0:1], 0, v[86:87]
	s_mov_b64 s[0:1], 0x1dd00000
	v_readlane_b32 s2, v254, 9
	v_bfe_u32 v4, v2, 4, 2
	v_lshl_add_u64 v[82:83], v[0:1], 0, s[0:1]
	v_lshlrev_b32_e32 v0, 2, v3
	s_add_u32 s36, s26, 0x1e500004
	v_readlane_b32 s3, v254, 10
	v_lshlrev_b32_e32 v103, 3, v4
	v_lshlrev_b32_e32 v88, 2, v4
	v_xor_b32_e32 v100, 64, v0
	v_xor_b32_e32 v101, 0x80, v0
	s_addc_u32 s37, s27, 0
	s_mov_b64 s[0:1], -1
	s_and_b64 vcc, exec, s[2:3]
	s_cbranch_vccnz .Lwin_generic
	v_readfirstlane_b32 s1, v143
	s_cmp_lt_u32 s1, 4
	s_cbranch_scc1 .Lw_prio_done
	s_setprio 1
.Lw_prio_done:
	v_mov_b32_e32 v53, v102
	v_mov_b32_e32 v54, v88
	v_mov_b32_e32 v55, v103
	v_mov_b32_e32 v64, v100
	v_mov_b32_e32 v66, v101
	s_lshr_b32 s21, s5, 3
	s_and_b32 s21, s21, 1
	s_lshl_b32 s20, s21, 3
	s_add_i32 s20, s20, s1
	s_lshl_b32 s39, s20, 7
	s_mul_i32 s56, s20, 6
	s_and_b32 s7, s5, 7
	s_lshl_b32 s7, s7, 7
	s_lshr_b32 s0, s5, 4
	s_and_b32 s0, s0, 15
	s_lshl_b32 s0, s0, 3
	s_add_i32 s7, s7, s0
	s_lshl_b32 s0, s21, 21
	s_add_i32 s2, s0, 0x1dd00000
	s_add_u32 s12, s26, s2
	s_addc_u32 s13, s27, 0
	s_add_i32 s2, s0, 0x1e100000
	s_add_u32 s14, s26, s2
	s_addc_u32 s15, s27, 0
	v_lshlrev_b32_e32 v51, 6, v53
	v_lshl_add_u32 v51, v55, 1, v51
	s_mov_b32 s40, 0x3e38aa3b
	s_mov_b32 s41, 0x3e38aa3b
	s_mov_b32 s57, 0x20400
	s_lshl_b32 s28, s1, 12
	v_and_b32_e32 v40, 63, v208
	v_add_u32_e32 v40, 0xffffffe0, v40
	v_lshlrev_b32_e32 v47, 2, v40
	v_add_u32_e32 v47, 0x80, v47
	v_add_u32_e32 v47, s28, v47
	v_mov_b32_e32 v46, 0xf149f2ca
	s_mov_b32 s0, 10

.Lw_exit:
	s_setprio 0
	s_waitcnt vmcnt(0)
	s_branch .LBB0_493

.LBB0_698:
	s_andn2_b64 vcc, exec, s[0:1]
	s_cbranch_vccnz .LBB0_992
	v_readlane_b32 s0, v254, 5
	v_readlane_b32 s1, v254, 6
	s_load_dwordx4 s[40:43], s[0:1], 0xa0
	s_load_dword s2, s[0:1], 0xb0
	v_mov_b32_e32 v0, v208
	s_waitcnt lgkmcnt(0)
	s_mov_b64 s[26:27], s[42:43]
	v_writelane_b32 v254, s2, 46
	v_ashrrev_i32_e32 v220, 6, v0
	v_readlane_b32 s2, v254, 0
	s_add_u32 s24, s26, 0x6d00000
	s_addc_u32 s25, s27, 0
	v_mov_b32_e32 v0, v208
	s_cmpk_gt_i32 s2, 0xff
	v_writelane_b32 v254, s2, 47
	s_cbranch_scc1 .LBB0_748
	s_cmpk_lg_i32 s46, 0x100
	s_cbranch_scc1 .Lintra_orig
	v_readlane_b32 s2, v254, 47
	v_readfirstlane_b32 s3, v220
	s_cmp_lt_u32 s3, 4
	s_cbranch_scc1 .Lintra_prio_done
	s_setprio 1
.Lintra_prio_done:
	s_load_dwordx2 s[28:29], s[0:1], 0x48
	v_readlane_b32 s6, v254, 39
	v_readlane_b32 s7, v254, 40
	s_lshr_b32 s4, s2, 6
	s_and_b32 s5, s2, 63
	v_and_b32_e32 v221, 15, v208
	v_bfe_u32 v222, v208, 4, 2
	v_lshlrev_b32_e32 v200, 6, v221
	v_lshl_add_u32 v200, v222, 4, v200
	v_mul_u32_u24_e32 v204, 0x1800, v221
	v_lshl_add_u32 v204, v222, 3, v204
	v_lshlrev_b32_e32 v205, 12, v221
	v_lshl_add_u32 v205, v222, 3, v205
	v_lshlrev_b32_e32 v206, 4, v222
	v_lshlrev_b32_e32 v223, 2, v222
	v_sub_u32_e32 v201, v221, v223
	v_mov_b32_e32 v231, v201
	v_and_b32_e32 v207, 63, v208
	v_lshlrev_b32_e32 v207, 4, v207
	v_add_u32_e32 v230, 0x10000, v207
	s_lshl_b32 s11, s3, 13
	s_lshl_b32 s0, s4, 23
	s_add_i32 s1, s0, 0xcd00000
	s_add_u32 s12, s26, s1
	s_addc_u32 s13, s27, 0
	s_add_i32 s1, s0, 0xed00000
	s_add_u32 s14, s26, s1
	s_addc_u32 s15, s27, 0
	s_lshl_b32 s0, s5, 17
	s_add_u32 s14, s14, s0
	s_addc_u32 s15, s15, 0
	s_lshl_b32 s0, s4, 24
	s_lshl_b32 s1, s5, 18
	s_add_i32 s0, s0, s1
	s_add_i32 s0, s0, 0x12d00000
	s_add_u32 s16, s26, s0
	s_addc_u32 s17, s27, 0
	s_lshl_b32 s0, s4, 6
	s_add_i32 s0, s0, s5
	s_lshl_b32 s0, s0, 18
	s_add_i32 s0, s0, 0x2d00000
	s_add_u32 s18, s26, s0
	s_addc_u32 s19, s27, 0
	s_lshl_b32 s0, s4, 10
	s_add_u32 s20, s24, s0
	s_addc_u32 s21, s25, 0
	s_add_i32 s1, s0, 0x16d00000
	s_add_u32 s22, s26, s1
	s_addc_u32 s23, s27, 0
	s_waitcnt lgkmcnt(0)
	s_add_u32 s28, s28, s6
	s_addc_u32 s29, s29, s7
	s_lshl_b32 s0, s4, 11
	s_add_u32 s28, s28, s0
	s_addc_u32 s29, s29, 0
	s_sub_i32 s1, 15, s3
	s_lshl_b32 s0, s5, 4
	s_add_i32 s8, s0, s3
	s_add_i32 s9, s0, s1
	s_lshr_b32 s6, s3, 1
	s_add_i32 s6, s6, 1
	s_lshr_b32 s7, s1, 1
	s_add_i32 s7, s7, 1
	s_lshl_b32 s0, s3, 4
	v_add_u32_e32 v201, s0, v231
	s_lshl_b32 s0, s1, 4
	v_add_u32_e32 v244, s0, v231
	s_lshl_b32 s0, s8, 13
	s_add_u32 s30, s12, s0
	s_addc_u32 s31, s13, 0
	global_load_dwordx4 v[0:3], v200, s[30:31] offset:0
	global_load_dwordx4 v[4:7], v200, s[30:31] offset:1024
	global_load_dwordx4 v[8:11], v200, s[30:31] offset:2048
	global_load_dwordx4 v[12:15], v200, s[30:31] offset:3072
	s_add_u32 s30, s30, 0x1000
	s_addc_u32 s31, s31, 0
	global_load_dwordx4 v[16:19], v200, s[30:31] offset:0
	global_load_dwordx4 v[20:23], v200, s[30:31] offset:1024
	global_load_dwordx4 v[24:27], v200, s[30:31] offset:2048
	global_load_dwordx4 v[28:31], v200, s[30:31] offset:3072
	s_lshl_b32 s0, s9, 13
	s_add_u32 s30, s12, s0
	s_addc_u32 s31, s13, 0
	global_load_dwordx4 v[168:171], v200, s[30:31] offset:0
	global_load_dwordx4 v[172:175], v200, s[30:31] offset:1024
	global_load_dwordx4 v[176:179], v200, s[30:31] offset:2048
	global_load_dwordx4 v[180:183], v200, s[30:31] offset:3072
	s_add_u32 s30, s30, 0x1000
	s_addc_u32 s31, s31, 0
	global_load_dwordx4 v[184:187], v200, s[30:31] offset:0
	global_load_dwordx4 v[188:191], v200, s[30:31] offset:1024
	global_load_dwordx4 v[192:195], v200, s[30:31] offset:2048
	global_load_dwordx4 v[196:199], v200, s[30:31] offset:3072
	s_lshl_b32 s8, s8, 4
	s_lshl_b32 s9, s9, 4
	s_lshl_b32 s0, s3, 14
	s_add_u32 s34, s14, s0
	s_addc_u32 s35, s15, 0
	s_add_i32 m0, s0, 0
	s_nop 0
	global_load_lds_dwordx4 v200, s[34:35]
	s_add_i32 m0, s0, 1024
	s_add_u32 s34, s34, 0x400
	s_addc_u32 s35, s35, 0
	global_load_lds_dwordx4 v200, s[34:35]
	s_add_i32 m0, s0, 2048
	s_add_u32 s34, s34, 0x400
	s_addc_u32 s35, s35, 0
	global_load_lds_dwordx4 v200, s[34:35]
	s_add_i32 m0, s0, 3072
	s_add_u32 s34, s34, 0x400
	s_addc_u32 s35, s35, 0
	global_load_lds_dwordx4 v200, s[34:35]
	s_add_i32 m0, s0, 4096
	s_add_u32 s34, s34, 0x400
	s_addc_u32 s35, s35, 0
	global_load_lds_dwordx4 v200, s[34:35]
	s_add_i32 m0, s0, 5120
	s_add_u32 s34, s34, 0x400
	s_addc_u32 s35, s35, 0
	global_load_lds_dwordx4 v200, s[34:35]
	s_add_i32 m0, s0, 6144
	s_add_u32 s34, s34, 0x400
	s_addc_u32 s35, s35, 0
	global_load_lds_dwordx4 v200, s[34:35]
	s_add_i32 m0, s0, 7168
	s_add_u32 s34, s34, 0x400
	s_addc_u32 s35, s35, 0
	global_load_lds_dwordx4 v200, s[34:35]
	s_add_i32 m0, s0, 8192
	s_add_u32 s34, s34, 0x400
	s_addc_u32 s35, s35, 0
	global_load_lds_dwordx4 v200, s[34:35]
	s_add_i32 m0, s0, 9216
	s_add_u32 s34, s34, 0x400
	s_addc_u32 s35, s35, 0
	global_load_lds_dwordx4 v200, s[34:35]
	s_add_i32 m0, s0, 10240
	s_add_u32 s34, s34, 0x400
	s_addc_u32 s35, s35, 0
	global_load_lds_dwordx4 v200, s[34:35]
	s_add_i32 m0, s0, 11264
	s_add_u32 s34, s34, 0x400
	s_addc_u32 s35, s35, 0
	global_load_lds_dwordx4 v200, s[34:35]
	s_add_i32 m0, s0, 12288
	s_add_u32 s34, s34, 0x400
	s_addc_u32 s35, s35, 0
	global_load_lds_dwordx4 v200, s[34:35]
	s_add_i32 m0, s0, 13312
	s_add_u32 s34, s34, 0x400
	s_addc_u32 s35, s35, 0
	global_load_lds_dwordx4 v200, s[34:35]
	s_add_i32 m0, s0, 14336
	s_add_u32 s34, s34, 0x400
	s_addc_u32 s35, s35, 0
	global_load_lds_dwordx4 v200, s[34:35]
	s_add_i32 m0, s0, 15360
	s_add_u32 s34, s34, 0x400
	s_addc_u32 s35, s35, 0
	global_load_lds_dwordx4 v200, s[34:35]
	s_waitcnt vmcnt(0)
	s_barrier
	ds_read_b128 v[100:103], v207 offset:0
	ds_read_b128 v[104:107], v207 offset:1024
	ds_read_b128 v[108:111], v207 offset:2048
	ds_read_b128 v[112:115], v207 offset:3072
	ds_read_b128 v[116:119], v207 offset:4096
	ds_read_b128 v[120:123], v207 offset:5120
	ds_read_b128 v[124:127], v207 offset:6144
	ds_read_b128 v[128:131], v207 offset:7168
	ds_read_b128 v[132:135], v207 offset:8192
	ds_read_b128 v[136:139], v207 offset:9216
	ds_read_b128 v[144:147], v207 offset:10240
	ds_read_b128 v[148:151], v207 offset:11264
	ds_read_b128 v[152:155], v207 offset:12288
	ds_read_b128 v[156:159], v207 offset:13312
	ds_read_b128 v[160:163], v207 offset:14336
	ds_read_b128 v[164:167], v207 offset:15360
	s_waitcnt lgkmcnt(8)
	v_mfma_f32_16x16x32_bf16 v[232:235], v[100:103], v[0:3], 0
	v_mfma_f32_16x16x32_bf16 v[232:235], v[104:107], v[4:7], v[232:235]
	v_mfma_f32_16x16x32_bf16 v[232:235], v[108:111], v[8:11], v[232:235]
	v_mfma_f32_16x16x32_bf16 v[232:235], v[112:115], v[12:15], v[232:235]
	v_mfma_f32_16x16x32_bf16 v[232:235], v[116:119], v[16:19], v[232:235]
	v_mfma_f32_16x16x32_bf16 v[232:235], v[120:123], v[20:23], v[232:235]
	v_mfma_f32_16x16x32_bf16 v[232:235], v[124:127], v[24:27], v[232:235]
	v_mfma_f32_16x16x32_bf16 v[232:235], v[128:131], v[28:31], v[232:235]
	s_waitcnt lgkmcnt(0)
	v_mfma_f32_16x16x32_bf16 v[236:239], v[132:135], v[0:3], 0
	v_mfma_f32_16x16x32_bf16 v[236:239], v[136:139], v[4:7], v[236:239]
	v_mfma_f32_16x16x32_bf16 v[236:239], v[144:147], v[8:11], v[236:239]
	v_mfma_f32_16x16x32_bf16 v[236:239], v[148:151], v[12:15], v[236:239]
	v_mfma_f32_16x16x32_bf16 v[236:239], v[152:155], v[16:19], v[236:239]
	v_mfma_f32_16x16x32_bf16 v[236:239], v[156:159], v[20:23], v[236:239]
	v_mfma_f32_16x16x32_bf16 v[236:239], v[160:163], v[24:27], v[236:239]
	v_mfma_f32_16x16x32_bf16 v[236:239], v[164:167], v[28:31], v[236:239]
	s_nop 7
	s_nop 3
	v_cmp_le_i32_e32 vcc, 0, v201
	s_nop 1
	v_cndmask_b32_e32 v232, 0, v232, vcc
	v_cmp_le_i32_e32 vcc, 1, v201
	s_nop 1
	v_cndmask_b32_e32 v233, 0, v233, vcc
	v_cmp_le_i32_e32 vcc, 2, v201
	s_nop 1
	v_cndmask_b32_e32 v234, 0, v234, vcc
	v_cmp_le_i32_e32 vcc, 3, v201
	s_nop 1
	v_cndmask_b32_e32 v235, 0, v235, vcc
	v_cmp_le_i32_e32 vcc, 16, v201
	s_nop 1
	v_cndmask_b32_e32 v236, 0, v236, vcc
	v_cmp_le_i32_e32 vcc, 17, v201
	s_nop 1
	v_cndmask_b32_e32 v237, 0, v237, vcc
	v_cmp_le_i32_e32 vcc, 18, v201
	s_nop 1
	v_cndmask_b32_e32 v238, 0, v238, vcc
	v_cmp_le_i32_e32 vcc, 19, v201
	s_nop 1
	v_cndmask_b32_e32 v239, 0, v239, vcc
	v_cvt_pk_bf16_f32 v32, v232, v233
	v_cvt_pk_bf16_f32 v33, v234, v235
	v_cvt_pk_bf16_f32 v34, v236, v237
	v_cvt_pk_bf16_f32 v35, v238, v239
	s_cmp_ge_i32 s6, 2
	s_cbranch_scc0 .Lintra_a0_done
	ds_read_b128 v[100:103], v207 offset:16384
	ds_read_b128 v[104:107], v207 offset:17408
	ds_read_b128 v[108:111], v207 offset:18432
	ds_read_b128 v[112:115], v207 offset:19456
	ds_read_b128 v[116:119], v207 offset:20480
	ds_read_b128 v[120:123], v207 offset:21504
	ds_read_b128 v[124:127], v207 offset:22528
	ds_read_b128 v[128:131], v207 offset:23552
	ds_read_b128 v[132:135], v207 offset:24576
	ds_read_b128 v[136:139], v207 offset:25600
	ds_read_b128 v[144:147], v207 offset:26624
	ds_read_b128 v[148:151], v207 offset:27648
	ds_read_b128 v[152:155], v207 offset:28672
	ds_read_b128 v[156:159], v207 offset:29696
	ds_read_b128 v[160:163], v207 offset:30720
	ds_read_b128 v[164:167], v207 offset:31744
	s_waitcnt lgkmcnt(8)
	v_mfma_f32_16x16x32_bf16 v[232:235], v[100:103], v[0:3], 0
	v_mfma_f32_16x16x32_bf16 v[232:235], v[104:107], v[4:7], v[232:235]
	v_mfma_f32_16x16x32_bf16 v[232:235], v[108:111], v[8:11], v[232:235]
	v_mfma_f32_16x16x32_bf16 v[232:235], v[112:115], v[12:15], v[232:235]
	v_mfma_f32_16x16x32_bf16 v[232:235], v[116:119], v[16:19], v[232:235]
	v_mfma_f32_16x16x32_bf16 v[232:235], v[120:123], v[20:23], v[232:235]
	v_mfma_f32_16x16x32_bf16 v[232:235], v[124:127], v[24:27], v[232:235]
	v_mfma_f32_16x16x32_bf16 v[232:235], v[128:131], v[28:31], v[232:235]
	s_waitcnt lgkmcnt(0)
	v_mfma_f32_16x16x32_bf16 v[236:239], v[132:135], v[0:3], 0
	v_mfma_f32_16x16x32_bf16 v[236:239], v[136:139], v[4:7], v[236:239]
	v_mfma_f32_16x16x32_bf16 v[236:239], v[144:147], v[8:11], v[236:239]
	v_mfma_f32_16x16x32_bf16 v[236:239], v[148:151], v[12:15], v[236:239]
	v_mfma_f32_16x16x32_bf16 v[236:239], v[152:155], v[16:19], v[236:239]
	v_mfma_f32_16x16x32_bf16 v[236:239], v[156:159], v[20:23], v[236:239]
	v_mfma_f32_16x16x32_bf16 v[236:239], v[160:163], v[24:27], v[236:239]
	v_mfma_f32_16x16x32_bf16 v[236:239], v[164:167], v[28:31], v[236:239]
	s_nop 7
	s_nop 3
	v_cmp_le_i32_e32 vcc, 32, v201
	s_nop 1
	v_cndmask_b32_e32 v232, 0, v232, vcc
	v_cmp_le_i32_e32 vcc, 33, v201
	s_nop 1
	v_cndmask_b32_e32 v233, 0, v233, vcc
	v_cmp_le_i32_e32 vcc, 34, v201
	s_nop 1
	v_cndmask_b32_e32 v234, 0, v234, vcc
	v_cmp_le_i32_e32 vcc, 35, v201
	s_nop 1
	v_cndmask_b32_e32 v235, 0, v235, vcc
	v_cmp_le_i32_e32 vcc, 48, v201
	s_nop 1
	v_cndmask_b32_e32 v236, 0, v236, vcc
	v_cmp_le_i32_e32 vcc, 49, v201
	s_nop 1
	v_cndmask_b32_e32 v237, 0, v237, vcc
	v_cmp_le_i32_e32 vcc, 50, v201
	s_nop 1
	v_cndmask_b32_e32 v238, 0, v238, vcc
	v_cmp_le_i32_e32 vcc, 51, v201
	s_nop 1
	v_cndmask_b32_e32 v239, 0, v239, vcc
	v_cvt_pk_bf16_f32 v36, v232, v233
	v_cvt_pk_bf16_f32 v37, v234, v235
	v_cvt_pk_bf16_f32 v38, v236, v237
	v_cvt_pk_bf16_f32 v39, v238, v239
	s_cmp_ge_i32 s6, 3
	s_cbranch_scc0 .Lintra_a0_done
	ds_read_b128 v[100:103], v207 offset:32768
	ds_read_b128 v[104:107], v207 offset:33792
	ds_read_b128 v[108:111], v207 offset:34816
	ds_read_b128 v[112:115], v207 offset:35840
	ds_read_b128 v[116:119], v207 offset:36864
	ds_read_b128 v[120:123], v207 offset:37888
	ds_read_b128 v[124:127], v207 offset:38912
	ds_read_b128 v[128:131], v207 offset:39936
	ds_read_b128 v[132:135], v207 offset:40960
	ds_read_b128 v[136:139], v207 offset:41984
	ds_read_b128 v[144:147], v207 offset:43008
	ds_read_b128 v[148:151], v207 offset:44032
	ds_read_b128 v[152:155], v207 offset:45056
	ds_read_b128 v[156:159], v207 offset:46080
	ds_read_b128 v[160:163], v207 offset:47104
	ds_read_b128 v[164:167], v207 offset:48128
	s_waitcnt lgkmcnt(8)
	v_mfma_f32_16x16x32_bf16 v[232:235], v[100:103], v[0:3], 0
	v_mfma_f32_16x16x32_bf16 v[232:235], v[104:107], v[4:7], v[232:235]
	v_mfma_f32_16x16x32_bf16 v[232:235], v[108:111], v[8:11], v[232:235]
	v_mfma_f32_16x16x32_bf16 v[232:235], v[112:115], v[12:15], v[232:235]
	v_mfma_f32_16x16x32_bf16 v[232:235], v[116:119], v[16:19], v[232:235]
	v_mfma_f32_16x16x32_bf16 v[232:235], v[120:123], v[20:23], v[232:235]
	v_mfma_f32_16x16x32_bf16 v[232:235], v[124:127], v[24:27], v[232:235]
	v_mfma_f32_16x16x32_bf16 v[232:235], v[128:131], v[28:31], v[232:235]
	s_waitcnt lgkmcnt(0)
	v_mfma_f32_16x16x32_bf16 v[236:239], v[132:135], v[0:3], 0
	v_mfma_f32_16x16x32_bf16 v[236:239], v[136:139], v[4:7], v[236:239]
	v_mfma_f32_16x16x32_bf16 v[236:239], v[144:147], v[8:11], v[236:239]
	v_mfma_f32_16x16x32_bf16 v[236:239], v[148:151], v[12:15], v[236:239]
	v_mfma_f32_16x16x32_bf16 v[236:239], v[152:155], v[16:19], v[236:239]
	v_mfma_f32_16x16x32_bf16 v[236:239], v[156:159], v[20:23], v[236:239]
	v_mfma_f32_16x16x32_bf16 v[236:239], v[160:163], v[24:27], v[236:239]
	v_mfma_f32_16x16x32_bf16 v[236:239], v[164:167], v[28:31], v[236:239]
	s_nop 7
	s_nop 3
	v_cmp_le_i32_e32 vcc, 64, v201
	s_nop 1
	v_cndmask_b32_e32 v232, 0, v232, vcc
	v_cmp_le_i32_e32 vcc, 65, v201
	s_nop 1
	v_cndmask_b32_e32 v233, 0, v233, vcc
	v_cmp_le_i32_e32 vcc, 66, v201
	s_nop 1
	v_cndmask_b32_e32 v234, 0, v234, vcc
	v_cmp_le_i32_e32 vcc, 67, v201
	s_nop 1
	v_cndmask_b32_e32 v235, 0, v235, vcc
	v_cmp_le_i32_e32 vcc, 80, v201
	s_nop 1
	v_cndmask_b32_e32 v236, 0, v236, vcc
	v_cmp_le_i32_e32 vcc, 81, v201
	s_nop 1
	v_cndmask_b32_e32 v237, 0, v237, vcc
	v_cmp_le_i32_e32 vcc, 82, v201
	s_nop 1
	v_cndmask_b32_e32 v238, 0, v238, vcc
	v_cmp_le_i32_e32 vcc, 83, v201
	s_nop 1
	v_cndmask_b32_e32 v239, 0, v239, vcc
	v_cvt_pk_bf16_f32 v40, v232, v233
	v_cvt_pk_bf16_f32 v41, v234, v235
	v_cvt_pk_bf16_f32 v42, v236, v237
	v_cvt_pk_bf16_f32 v43, v238, v239
	s_cmp_ge_i32 s6, 4
	s_cbranch_scc0 .Lintra_a0_done
	ds_read_b128 v[100:103], v207 offset:49152
	ds_read_b128 v[104:107], v207 offset:50176
	ds_read_b128 v[108:111], v207 offset:51200
	ds_read_b128 v[112:115], v207 offset:52224
	ds_read_b128 v[116:119], v207 offset:53248
	ds_read_b128 v[120:123], v207 offset:54272
	ds_read_b128 v[124:127], v207 offset:55296
	ds_read_b128 v[128:131], v207 offset:56320
	ds_read_b128 v[132:135], v207 offset:57344
	ds_read_b128 v[136:139], v207 offset:58368
	ds_read_b128 v[144:147], v207 offset:59392
	ds_read_b128 v[148:151], v207 offset:60416
	ds_read_b128 v[152:155], v207 offset:61440
	ds_read_b128 v[156:159], v207 offset:62464
	ds_read_b128 v[160:163], v207 offset:63488
	ds_read_b128 v[164:167], v207 offset:64512
	s_waitcnt lgkmcnt(8)
	v_mfma_f32_16x16x32_bf16 v[232:235], v[100:103], v[0:3], 0
	v_mfma_f32_16x16x32_bf16 v[232:235], v[104:107], v[4:7], v[232:235]
	v_mfma_f32_16x16x32_bf16 v[232:235], v[108:111], v[8:11], v[232:235]
	v_mfma_f32_16x16x32_bf16 v[232:235], v[112:115], v[12:15], v[232:235]
	v_mfma_f32_16x16x32_bf16 v[232:235], v[116:119], v[16:19], v[232:235]
	v_mfma_f32_16x16x32_bf16 v[232:235], v[120:123], v[20:23], v[232:235]
	v_mfma_f32_16x16x32_bf16 v[232:235], v[124:127], v[24:27], v[232:235]
	v_mfma_f32_16x16x32_bf16 v[232:235], v[128:131], v[28:31], v[232:235]
	s_waitcnt lgkmcnt(0)
	v_mfma_f32_16x16x32_bf16 v[236:239], v[132:135], v[0:3], 0
	v_mfma_f32_16x16x32_bf16 v[236:239], v[136:139], v[4:7], v[236:239]
	v_mfma_f32_16x16x32_bf16 v[236:239], v[144:147], v[8:11], v[236:239]
	v_mfma_f32_16x16x32_bf16 v[236:239], v[148:151], v[12:15], v[236:239]
	v_mfma_f32_16x16x32_bf16 v[236:239], v[152:155], v[16:19], v[236:239]
	v_mfma_f32_16x16x32_bf16 v[236:239], v[156:159], v[20:23], v[236:239]
	v_mfma_f32_16x16x32_bf16 v[236:239], v[160:163], v[24:27], v[236:239]
	v_mfma_f32_16x16x32_bf16 v[236:239], v[164:167], v[28:31], v[236:239]
	s_nop 7
	s_nop 3
	v_cmp_le_i32_e32 vcc, 96, v201
	s_nop 1
	v_cndmask_b32_e32 v232, 0, v232, vcc
	v_cmp_le_i32_e32 vcc, 97, v201
	s_nop 1
	v_cndmask_b32_e32 v233, 0, v233, vcc
	v_cmp_le_i32_e32 vcc, 98, v201
	s_nop 1
	v_cndmask_b32_e32 v234, 0, v234, vcc
	v_cmp_le_i32_e32 vcc, 99, v201
	s_nop 1
	v_cndmask_b32_e32 v235, 0, v235, vcc
	v_cmp_le_i32_e32 vcc, 112, v201
	s_nop 1
	v_cndmask_b32_e32 v236, 0, v236, vcc
	v_cmp_le_i32_e32 vcc, 113, v201
	s_nop 1
	v_cndmask_b32_e32 v237, 0, v237, vcc
	v_cmp_le_i32_e32 vcc, 114, v201
	s_nop 1
	v_cndmask_b32_e32 v238, 0, v238, vcc
	v_cmp_le_i32_e32 vcc, 115, v201
	s_nop 1
	v_cndmask_b32_e32 v239, 0, v239, vcc
	v_cvt_pk_bf16_f32 v44, v232, v233
	v_cvt_pk_bf16_f32 v45, v234, v235
	v_cvt_pk_bf16_f32 v46, v236, v237
	v_cvt_pk_bf16_f32 v47, v238, v239
	s_cmp_ge_i32 s6, 5
	s_cbranch_scc0 .Lintra_a0_done
	ds_read_b128 v[100:103], v230 offset:0
	ds_read_b128 v[104:107], v230 offset:1024
	ds_read_b128 v[108:111], v230 offset:2048
	ds_read_b128 v[112:115], v230 offset:3072
	ds_read_b128 v[116:119], v230 offset:4096
	ds_read_b128 v[120:123], v230 offset:5120
	ds_read_b128 v[124:127], v230 offset:6144
	ds_read_b128 v[128:131], v230 offset:7168
	ds_read_b128 v[132:135], v230 offset:8192
	ds_read_b128 v[136:139], v230 offset:9216
	ds_read_b128 v[144:147], v230 offset:10240
	ds_read_b128 v[148:151], v230 offset:11264
	ds_read_b128 v[152:155], v230 offset:12288
	ds_read_b128 v[156:159], v230 offset:13312
	ds_read_b128 v[160:163], v230 offset:14336
	ds_read_b128 v[164:167], v230 offset:15360
	s_waitcnt lgkmcnt(8)
	v_mfma_f32_16x16x32_bf16 v[232:235], v[100:103], v[0:3], 0
	v_mfma_f32_16x16x32_bf16 v[232:235], v[104:107], v[4:7], v[232:235]
	v_mfma_f32_16x16x32_bf16 v[232:235], v[108:111], v[8:11], v[232:235]
	v_mfma_f32_16x16x32_bf16 v[232:235], v[112:115], v[12:15], v[232:235]
	v_mfma_f32_16x16x32_bf16 v[232:235], v[116:119], v[16:19], v[232:235]
	v_mfma_f32_16x16x32_bf16 v[232:235], v[120:123], v[20:23], v[232:235]
	v_mfma_f32_16x16x32_bf16 v[232:235], v[124:127], v[24:27], v[232:235]
	v_mfma_f32_16x16x32_bf16 v[232:235], v[128:131], v[28:31], v[232:235]
	s_waitcnt lgkmcnt(0)
	v_mfma_f32_16x16x32_bf16 v[236:239], v[132:135], v[0:3], 0
	v_mfma_f32_16x16x32_bf16 v[236:239], v[136:139], v[4:7], v[236:239]
	v_mfma_f32_16x16x32_bf16 v[236:239], v[144:147], v[8:11], v[236:239]
	v_mfma_f32_16x16x32_bf16 v[236:239], v[148:151], v[12:15], v[236:239]
	v_mfma_f32_16x16x32_bf16 v[236:239], v[152:155], v[16:19], v[236:239]
	v_mfma_f32_16x16x32_bf16 v[236:239], v[156:159], v[20:23], v[236:239]
	v_mfma_f32_16x16x32_bf16 v[236:239], v[160:163], v[24:27], v[236:239]
	v_mfma_f32_16x16x32_bf16 v[236:239], v[164:167], v[28:31], v[236:239]
	s_nop 7
	s_nop 3
	v_cmp_le_i32_e32 vcc, 128, v201
	s_nop 1
	v_cndmask_b32_e32 v232, 0, v232, vcc
	v_cmp_le_i32_e32 vcc, 129, v201
	s_nop 1
	v_cndmask_b32_e32 v233, 0, v233, vcc
	v_cmp_le_i32_e32 vcc, 130, v201
	s_nop 1
	v_cndmask_b32_e32 v234, 0, v234, vcc
	v_cmp_le_i32_e32 vcc, 131, v201
	s_nop 1
	v_cndmask_b32_e32 v235, 0, v235, vcc
	v_cmp_le_i32_e32 vcc, 144, v201
	s_nop 1
	v_cndmask_b32_e32 v236, 0, v236, vcc
	v_cmp_le_i32_e32 vcc, 145, v201
	s_nop 1
	v_cndmask_b32_e32 v237, 0, v237, vcc
	v_cmp_le_i32_e32 vcc, 146, v201
	s_nop 1
	v_cndmask_b32_e32 v238, 0, v238, vcc
	v_cmp_le_i32_e32 vcc, 147, v201
	s_nop 1
	v_cndmask_b32_e32 v239, 0, v239, vcc
	v_cvt_pk_bf16_f32 v48, v232, v233
	v_cvt_pk_bf16_f32 v49, v234, v235
	v_cvt_pk_bf16_f32 v50, v236, v237
	v_cvt_pk_bf16_f32 v51, v238, v239
	s_cmp_ge_i32 s6, 6
	s_cbranch_scc0 .Lintra_a0_done
	ds_read_b128 v[100:103], v230 offset:16384
	ds_read_b128 v[104:107], v230 offset:17408
	ds_read_b128 v[108:111], v230 offset:18432
	ds_read_b128 v[112:115], v230 offset:19456
	ds_read_b128 v[116:119], v230 offset:20480
	ds_read_b128 v[120:123], v230 offset:21504
	ds_read_b128 v[124:127], v230 offset:22528
	ds_read_b128 v[128:131], v230 offset:23552
	ds_read_b128 v[132:135], v230 offset:24576
	ds_read_b128 v[136:139], v230 offset:25600
	ds_read_b128 v[144:147], v230 offset:26624
	ds_read_b128 v[148:151], v230 offset:27648
	ds_read_b128 v[152:155], v230 offset:28672
	ds_read_b128 v[156:159], v230 offset:29696
	ds_read_b128 v[160:163], v230 offset:30720
	ds_read_b128 v[164:167], v230 offset:31744
	s_waitcnt lgkmcnt(8)
	v_mfma_f32_16x16x32_bf16 v[232:235], v[100:103], v[0:3], 0
	v_mfma_f32_16x16x32_bf16 v[232:235], v[104:107], v[4:7], v[232:235]
	v_mfma_f32_16x16x32_bf16 v[232:235], v[108:111], v[8:11], v[232:235]
	v_mfma_f32_16x16x32_bf16 v[232:235], v[112:115], v[12:15], v[232:235]
	v_mfma_f32_16x16x32_bf16 v[232:235], v[116:119], v[16:19], v[232:235]
	v_mfma_f32_16x16x32_bf16 v[232:235], v[120:123], v[20:23], v[232:235]
	v_mfma_f32_16x16x32_bf16 v[232:235], v[124:127], v[24:27], v[232:235]
	v_mfma_f32_16x16x32_bf16 v[232:235], v[128:131], v[28:31], v[232:235]
	s_waitcnt lgkmcnt(0)
	v_mfma_f32_16x16x32_bf16 v[236:239], v[132:135], v[0:3], 0
	v_mfma_f32_16x16x32_bf16 v[236:239], v[136:139], v[4:7], v[236:239]
	v_mfma_f32_16x16x32_bf16 v[236:239], v[144:147], v[8:11], v[236:239]
	v_mfma_f32_16x16x32_bf16 v[236:239], v[148:151], v[12:15], v[236:239]
	v_mfma_f32_16x16x32_bf16 v[236:239], v[152:155], v[16:19], v[236:239]
	v_mfma_f32_16x16x32_bf16 v[236:239], v[156:159], v[20:23], v[236:239]
	v_mfma_f32_16x16x32_bf16 v[236:239], v[160:163], v[24:27], v[236:239]
	v_mfma_f32_16x16x32_bf16 v[236:239], v[164:167], v[28:31], v[236:239]
	s_nop 7
	s_nop 3
	v_cmp_le_i32_e32 vcc, 160, v201
	s_nop 1
	v_cndmask_b32_e32 v232, 0, v232, vcc
	v_cmp_le_i32_e32 vcc, 161, v201
	s_nop 1
	v_cndmask_b32_e32 v233, 0, v233, vcc
	v_cmp_le_i32_e32 vcc, 162, v201
	s_nop 1
	v_cndmask_b32_e32 v234, 0, v234, vcc
	v_cmp_le_i32_e32 vcc, 163, v201
	s_nop 1
	v_cndmask_b32_e32 v235, 0, v235, vcc
	v_cmp_le_i32_e32 vcc, 176, v201
	s_nop 1
	v_cndmask_b32_e32 v236, 0, v236, vcc
	v_cmp_le_i32_e32 vcc, 177, v201
	s_nop 1
	v_cndmask_b32_e32 v237, 0, v237, vcc
	v_cmp_le_i32_e32 vcc, 178, v201
	s_nop 1
	v_cndmask_b32_e32 v238, 0, v238, vcc
	v_cmp_le_i32_e32 vcc, 179, v201
	s_nop 1
	v_cndmask_b32_e32 v239, 0, v239, vcc
	v_cvt_pk_bf16_f32 v52, v232, v233
	v_cvt_pk_bf16_f32 v53, v234, v235
	v_cvt_pk_bf16_f32 v54, v236, v237
	v_cvt_pk_bf16_f32 v55, v238, v239
	s_cmp_ge_i32 s6, 7
	s_cbranch_scc0 .Lintra_a0_done
	ds_read_b128 v[100:103], v230 offset:32768
	ds_read_b128 v[104:107], v230 offset:33792
	ds_read_b128 v[108:111], v230 offset:34816
	ds_read_b128 v[112:115], v230 offset:35840
	ds_read_b128 v[116:119], v230 offset:36864
	ds_read_b128 v[120:123], v230 offset:37888
	ds_read_b128 v[124:127], v230 offset:38912
	ds_read_b128 v[128:131], v230 offset:39936
	ds_read_b128 v[132:135], v230 offset:40960
	ds_read_b128 v[136:139], v230 offset:41984
	ds_read_b128 v[144:147], v230 offset:43008
	ds_read_b128 v[148:151], v230 offset:44032
	ds_read_b128 v[152:155], v230 offset:45056
	ds_read_b128 v[156:159], v230 offset:46080
	ds_read_b128 v[160:163], v230 offset:47104
	ds_read_b128 v[164:167], v230 offset:48128
	s_waitcnt lgkmcnt(8)
	v_mfma_f32_16x16x32_bf16 v[232:235], v[100:103], v[0:3], 0
	v_mfma_f32_16x16x32_bf16 v[232:235], v[104:107], v[4:7], v[232:235]
	v_mfma_f32_16x16x32_bf16 v[232:235], v[108:111], v[8:11], v[232:235]
	v_mfma_f32_16x16x32_bf16 v[232:235], v[112:115], v[12:15], v[232:235]
	v_mfma_f32_16x16x32_bf16 v[232:235], v[116:119], v[16:19], v[232:235]
	v_mfma_f32_16x16x32_bf16 v[232:235], v[120:123], v[20:23], v[232:235]
	v_mfma_f32_16x16x32_bf16 v[232:235], v[124:127], v[24:27], v[232:235]
	v_mfma_f32_16x16x32_bf16 v[232:235], v[128:131], v[28:31], v[232:235]
	s_waitcnt lgkmcnt(0)
	v_mfma_f32_16x16x32_bf16 v[236:239], v[132:135], v[0:3], 0
	v_mfma_f32_16x16x32_bf16 v[236:239], v[136:139], v[4:7], v[236:239]
	v_mfma_f32_16x16x32_bf16 v[236:239], v[144:147], v[8:11], v[236:239]
	v_mfma_f32_16x16x32_bf16 v[236:239], v[148:151], v[12:15], v[236:239]
	v_mfma_f32_16x16x32_bf16 v[236:239], v[152:155], v[16:19], v[236:239]
	v_mfma_f32_16x16x32_bf16 v[236:239], v[156:159], v[20:23], v[236:239]
	v_mfma_f32_16x16x32_bf16 v[236:239], v[160:163], v[24:27], v[236:239]
	v_mfma_f32_16x16x32_bf16 v[236:239], v[164:167], v[28:31], v[236:239]
	s_nop 7
	s_nop 3
	v_cmp_le_i32_e32 vcc, 192, v201
	s_nop 1
	v_cndmask_b32_e32 v232, 0, v232, vcc
	v_cmp_le_i32_e32 vcc, 193, v201
	s_nop 1
	v_cndmask_b32_e32 v233, 0, v233, vcc
	v_cmp_le_i32_e32 vcc, 194, v201
	s_nop 1
	v_cndmask_b32_e32 v234, 0, v234, vcc
	v_cmp_le_i32_e32 vcc, 195, v201
	s_nop 1
	v_cndmask_b32_e32 v235, 0, v235, vcc
	v_cmp_le_i32_e32 vcc, 208, v201
	s_nop 1
	v_cndmask_b32_e32 v236, 0, v236, vcc
	v_cmp_le_i32_e32 vcc, 209, v201
	s_nop 1
	v_cndmask_b32_e32 v237, 0, v237, vcc
	v_cmp_le_i32_e32 vcc, 210, v201
	s_nop 1
	v_cndmask_b32_e32 v238, 0, v238, vcc
	v_cmp_le_i32_e32 vcc, 211, v201
	s_nop 1
	v_cndmask_b32_e32 v239, 0, v239, vcc
	v_cvt_pk_bf16_f32 v56, v232, v233
	v_cvt_pk_bf16_f32 v57, v234, v235
	v_cvt_pk_bf16_f32 v58, v236, v237
	v_cvt_pk_bf16_f32 v59, v238, v239
	s_cmp_ge_i32 s6, 8
	s_cbranch_scc0 .Lintra_a0_done
	ds_read_b128 v[100:103], v230 offset:49152
	ds_read_b128 v[104:107], v230 offset:50176
	ds_read_b128 v[108:111], v230 offset:51200
	ds_read_b128 v[112:115], v230 offset:52224
	ds_read_b128 v[116:119], v230 offset:53248
	ds_read_b128 v[120:123], v230 offset:54272
	ds_read_b128 v[124:127], v230 offset:55296
	ds_read_b128 v[128:131], v230 offset:56320
	ds_read_b128 v[132:135], v230 offset:57344
	ds_read_b128 v[136:139], v230 offset:58368
	ds_read_b128 v[144:147], v230 offset:59392
	ds_read_b128 v[148:151], v230 offset:60416
	ds_read_b128 v[152:155], v230 offset:61440
	ds_read_b128 v[156:159], v230 offset:62464
	ds_read_b128 v[160:163], v230 offset:63488
	ds_read_b128 v[164:167], v230 offset:64512
	s_waitcnt lgkmcnt(8)
	v_mfma_f32_16x16x32_bf16 v[232:235], v[100:103], v[0:3], 0
	v_mfma_f32_16x16x32_bf16 v[232:235], v[104:107], v[4:7], v[232:235]
	v_mfma_f32_16x16x32_bf16 v[232:235], v[108:111], v[8:11], v[232:235]
	v_mfma_f32_16x16x32_bf16 v[232:235], v[112:115], v[12:15], v[232:235]
	v_mfma_f32_16x16x32_bf16 v[232:235], v[116:119], v[16:19], v[232:235]
	v_mfma_f32_16x16x32_bf16 v[232:235], v[120:123], v[20:23], v[232:235]
	v_mfma_f32_16x16x32_bf16 v[232:235], v[124:127], v[24:27], v[232:235]
	v_mfma_f32_16x16x32_bf16 v[232:235], v[128:131], v[28:31], v[232:235]
	s_waitcnt lgkmcnt(0)
	v_mfma_f32_16x16x32_bf16 v[236:239], v[132:135], v[0:3], 0
	v_mfma_f32_16x16x32_bf16 v[236:239], v[136:139], v[4:7], v[236:239]
	v_mfma_f32_16x16x32_bf16 v[236:239], v[144:147], v[8:11], v[236:239]
	v_mfma_f32_16x16x32_bf16 v[236:239], v[148:151], v[12:15], v[236:239]
	v_mfma_f32_16x16x32_bf16 v[236:239], v[152:155], v[16:19], v[236:239]
	v_mfma_f32_16x16x32_bf16 v[236:239], v[156:159], v[20:23], v[236:239]
	v_mfma_f32_16x16x32_bf16 v[236:239], v[160:163], v[24:27], v[236:239]
	v_mfma_f32_16x16x32_bf16 v[236:239], v[164:167], v[28:31], v[236:239]
	s_nop 7
	s_nop 3
	v_cmp_le_i32_e32 vcc, 224, v201
	s_nop 1
	v_cndmask_b32_e32 v232, 0, v232, vcc
	v_cmp_le_i32_e32 vcc, 225, v201
	s_nop 1
	v_cndmask_b32_e32 v233, 0, v233, vcc
	v_cmp_le_i32_e32 vcc, 226, v201
	s_nop 1
	v_cndmask_b32_e32 v234, 0, v234, vcc
	v_cmp_le_i32_e32 vcc, 227, v201
	s_nop 1
	v_cndmask_b32_e32 v235, 0, v235, vcc
	v_cmp_le_i32_e32 vcc, 240, v201
	s_nop 1
	v_cndmask_b32_e32 v236, 0, v236, vcc
	v_cmp_le_i32_e32 vcc, 241, v201
	s_nop 1
	v_cndmask_b32_e32 v237, 0, v237, vcc
	v_cmp_le_i32_e32 vcc, 242, v201
	s_nop 1
	v_cndmask_b32_e32 v238, 0, v238, vcc
	v_cmp_le_i32_e32 vcc, 243, v201
	s_nop 1
	v_cndmask_b32_e32 v239, 0, v239, vcc
	v_cvt_pk_bf16_f32 v60, v232, v233
	v_cvt_pk_bf16_f32 v61, v234, v235
	v_cvt_pk_bf16_f32 v62, v236, v237
	v_cvt_pk_bf16_f32 v63, v238, v239

.Lintra_c_go:
	v_mov_b32_e32 v221, v208
	v_and_b32_e32 v221, 63, v221
	v_lshlrev_b32_e32 v221, 2, v221
	v_xor_b32_e32 v222, 64, v221
	v_xor_b32_e32 v221, 0x80, v221
	ds_bpermute_b32 v223, v222, v202
	ds_bpermute_b32 v224, v222, v203
	s_waitcnt lgkmcnt(0)
	v_add_f32_e32 v202, v202, v223
	v_add_f32_e32 v203, v203, v224
	ds_bpermute_b32 v223, v221, v202
	ds_bpermute_b32 v224, v221, v203
	s_waitcnt lgkmcnt(0)
	v_add_f32_e32 v202, v202, v223
	v_add_f32_e32 v203, v203, v224
	v_mul_f32_e32 v227, 0x3b000000, v202
	v_mul_f32_e32 v228, 0x3b000000, v203
	v_fma_f32 v228, -v227, v227, v228
	v_max_f32_e32 v228, 0, v228
	v_add_f32_e32 v228, 0x3727c5ac, v228
	v_rsq_f32_e32 v228, v228
	s_mul_i32 s0, s8, 0x1800
	s_add_u32 s30, s20, s0
	s_addc_u32 s31, s21, 0
	s_lshl_b32 s0, s8, 12
	s_add_u32 s34, s22, s0
	s_addc_u32 s35, s23, 0
	s_waitcnt vmcnt(0)
	global_load_dwordx2 v[24:25], v205, s[34:35] offset:0
	global_load_dwordx2 v[100:101], v204, s[30:31] offset:0
	global_load_dwordx4 v[68:71], v206, s[28:29] offset:0
	global_load_dwordx2 v[26:27], v205, s[34:35] offset:32
	global_load_dwordx2 v[102:103], v204, s[30:31] offset:32
	global_load_dwordx4 v[72:75], v206, s[28:29] offset:64
	global_load_dwordx2 v[28:29], v205, s[34:35] offset:64
	global_load_dwordx2 v[104:105], v204, s[30:31] offset:64
	global_load_dwordx4 v[76:79], v206, s[28:29] offset:128
	global_load_dwordx2 v[30:31], v205, s[34:35] offset:96
	global_load_dwordx2 v[106:107], v204, s[30:31] offset:96
	global_load_dwordx4 v[80:83], v206, s[28:29] offset:192
	global_load_dwordx2 v[32:33], v205, s[34:35] offset:128
	global_load_dwordx2 v[108:109], v204, s[30:31] offset:128
	global_load_dwordx4 v[84:87], v206, s[28:29] offset:256
	global_load_dwordx2 v[34:35], v205, s[34:35] offset:160
	global_load_dwordx2 v[110:111], v204, s[30:31] offset:160
	global_load_dwordx4 v[88:91], v206, s[28:29] offset:320
	global_load_dwordx2 v[36:37], v205, s[34:35] offset:192
	global_load_dwordx2 v[112:113], v204, s[30:31] offset:192
	global_load_dwordx4 v[92:95], v206, s[28:29] offset:384
	global_load_dwordx2 v[38:39], v205, s[34:35] offset:224
	global_load_dwordx2 v[114:115], v204, s[30:31] offset:224
	global_load_dwordx4 v[96:99], v206, s[28:29] offset:448
	global_load_dwordx2 v[40:41], v205, s[34:35] offset:256
	global_load_dwordx2 v[116:117], v204, s[30:31] offset:256
	global_load_dwordx4 v[132:135], v206, s[28:29] offset:512
	global_load_dwordx2 v[42:43], v205, s[34:35] offset:288
	global_load_dwordx2 v[118:119], v204, s[30:31] offset:288
	global_load_dwordx4 v[136:139], v206, s[28:29] offset:576
	global_load_dwordx2 v[44:45], v205, s[34:35] offset:320
	global_load_dwordx2 v[120:121], v204, s[30:31] offset:320
	global_load_dwordx4 v[144:147], v206, s[28:29] offset:640
	global_load_dwordx2 v[46:47], v205, s[34:35] offset:352
	global_load_dwordx2 v[122:123], v204, s[30:31] offset:352
	global_load_dwordx4 v[148:151], v206, s[28:29] offset:704
	global_load_dwordx2 v[48:49], v205, s[34:35] offset:384
	global_load_dwordx2 v[124:125], v204, s[30:31] offset:384
	global_load_dwordx4 v[152:155], v206, s[28:29] offset:768
	global_load_dwordx2 v[50:51], v205, s[34:35] offset:416
	global_load_dwordx2 v[126:127], v204, s[30:31] offset:416
	global_load_dwordx4 v[156:159], v206, s[28:29] offset:832
	global_load_dwordx2 v[52:53], v205, s[34:35] offset:448
	global_load_dwordx2 v[128:129], v204, s[30:31] offset:448
	global_load_dwordx4 v[160:163], v206, s[28:29] offset:896
	global_load_dwordx2 v[54:55], v205, s[34:35] offset:480
	global_load_dwordx2 v[130:131], v204, s[30:31] offset:480
	global_load_dwordx4 v[164:167], v206, s[28:29] offset:960
	s_waitcnt vmcnt(45)
	v_lshlrev_b32_e32 v12, 16, v24
	v_and_b32_e32 v13, 0xffff0000, v24
	v_lshlrev_b32_e32 v14, 16, v25
	v_and_b32_e32 v15, 0xffff0000, v25
	v_mul_f32_e32 v16, 0xbfb8aa3b, v12
	v_mul_f32_e32 v17, 0xbfb8aa3b, v13
	v_mul_f32_e32 v18, 0xbfb8aa3b, v14
	v_mul_f32_e32 v19, 0xbfb8aa3b, v15
	v_exp_f32_e32 v16, v16
	v_exp_f32_e32 v17, v17
	v_exp_f32_e32 v18, v18
	v_exp_f32_e32 v19, v19
	v_lshlrev_b32_e32 v20, 16, v100
	v_and_b32_e32 v21, 0xffff0000, v100
	v_lshlrev_b32_e32 v22, 16, v101
	v_and_b32_e32 v23, 0xffff0000, v101
	v_add_f32_e32 v16, 1.0, v16
	v_add_f32_e32 v17, 1.0, v17
	v_add_f32_e32 v18, 1.0, v18
	v_add_f32_e32 v19, 1.0, v19
	v_rcp_f32_e32 v16, v16
	v_rcp_f32_e32 v17, v17
	v_rcp_f32_e32 v18, v18
	v_rcp_f32_e32 v19, v19
	v_sub_f32_e32 v20, v20, v227
	v_sub_f32_e32 v21, v21, v227
	v_sub_f32_e32 v22, v22, v227
	v_sub_f32_e32 v23, v23, v227
	v_mul_f32_e32 v20, v20, v228
	v_mul_f32_e32 v21, v21, v228
	v_mul_f32_e32 v22, v22, v228
	v_mul_f32_e32 v23, v23, v228
	v_mul_f32_e32 v12, v12, v16
	v_mul_f32_e32 v13, v13, v17
	v_mul_f32_e32 v14, v14, v18
	v_mul_f32_e32 v15, v15, v19
	v_mul_f32_e32 v20, v20, v68
	v_mul_f32_e32 v21, v21, v69
	v_mul_f32_e32 v22, v22, v70
	v_mul_f32_e32 v23, v23, v71
	v_mul_f32_e32 v20, v20, v12
	v_mul_f32_e32 v21, v21, v13
	v_mul_f32_e32 v22, v22, v14
	v_mul_f32_e32 v23, v23, v15
	v_cvt_pk_bf16_f32 v20, v20, v21
	v_cvt_pk_bf16_f32 v21, v22, v23
	global_store_dwordx2 v204, v[20:21], s[30:31] offset:0
	s_waitcnt vmcnt(43)
	v_lshlrev_b32_e32 v12, 16, v26
	v_and_b32_e32 v13, 0xffff0000, v26
	v_lshlrev_b32_e32 v14, 16, v27
	v_and_b32_e32 v15, 0xffff0000, v27
	v_mul_f32_e32 v16, 0xbfb8aa3b, v12
	v_mul_f32_e32 v17, 0xbfb8aa3b, v13
	v_mul_f32_e32 v18, 0xbfb8aa3b, v14
	v_mul_f32_e32 v19, 0xbfb8aa3b, v15
	v_exp_f32_e32 v16, v16
	v_exp_f32_e32 v17, v17
	v_exp_f32_e32 v18, v18
	v_exp_f32_e32 v19, v19
	v_lshlrev_b32_e32 v20, 16, v102
	v_and_b32_e32 v21, 0xffff0000, v102
	v_lshlrev_b32_e32 v22, 16, v103
	v_and_b32_e32 v23, 0xffff0000, v103
	v_add_f32_e32 v16, 1.0, v16
	v_add_f32_e32 v17, 1.0, v17
	v_add_f32_e32 v18, 1.0, v18
	v_add_f32_e32 v19, 1.0, v19
	v_rcp_f32_e32 v16, v16
	v_rcp_f32_e32 v17, v17
	v_rcp_f32_e32 v18, v18
	v_rcp_f32_e32 v19, v19
	v_sub_f32_e32 v20, v20, v227
	v_sub_f32_e32 v21, v21, v227
	v_sub_f32_e32 v22, v22, v227
	v_sub_f32_e32 v23, v23, v227
	v_mul_f32_e32 v20, v20, v228
	v_mul_f32_e32 v21, v21, v228
	v_mul_f32_e32 v22, v22, v228
	v_mul_f32_e32 v23, v23, v228
	v_mul_f32_e32 v12, v12, v16
	v_mul_f32_e32 v13, v13, v17
	v_mul_f32_e32 v14, v14, v18
	v_mul_f32_e32 v15, v15, v19
	v_mul_f32_e32 v20, v20, v72
	v_mul_f32_e32 v21, v21, v73
	v_mul_f32_e32 v22, v22, v74
	v_mul_f32_e32 v23, v23, v75
	v_mul_f32_e32 v20, v20, v12
	v_mul_f32_e32 v21, v21, v13
	v_mul_f32_e32 v22, v22, v14
	v_mul_f32_e32 v23, v23, v15
	v_cvt_pk_bf16_f32 v20, v20, v21
	v_cvt_pk_bf16_f32 v21, v22, v23
	global_store_dwordx2 v204, v[20:21], s[30:31] offset:32
	s_waitcnt vmcnt(41)
	v_lshlrev_b32_e32 v12, 16, v28
	v_and_b32_e32 v13, 0xffff0000, v28
	v_lshlrev_b32_e32 v14, 16, v29
	v_and_b32_e32 v15, 0xffff0000, v29
	v_mul_f32_e32 v16, 0xbfb8aa3b, v12
	v_mul_f32_e32 v17, 0xbfb8aa3b, v13
	v_mul_f32_e32 v18, 0xbfb8aa3b, v14
	v_mul_f32_e32 v19, 0xbfb8aa3b, v15
	v_exp_f32_e32 v16, v16
	v_exp_f32_e32 v17, v17
	v_exp_f32_e32 v18, v18
	v_exp_f32_e32 v19, v19
	v_lshlrev_b32_e32 v20, 16, v104
	v_and_b32_e32 v21, 0xffff0000, v104
	v_lshlrev_b32_e32 v22, 16, v105
	v_and_b32_e32 v23, 0xffff0000, v105
	v_add_f32_e32 v16, 1.0, v16
	v_add_f32_e32 v17, 1.0, v17
	v_add_f32_e32 v18, 1.0, v18
	v_add_f32_e32 v19, 1.0, v19
	v_rcp_f32_e32 v16, v16
	v_rcp_f32_e32 v17, v17
	v_rcp_f32_e32 v18, v18
	v_rcp_f32_e32 v19, v19
	v_sub_f32_e32 v20, v20, v227
	v_sub_f32_e32 v21, v21, v227
	v_sub_f32_e32 v22, v22, v227
	v_sub_f32_e32 v23, v23, v227
	v_mul_f32_e32 v20, v20, v228
	v_mul_f32_e32 v21, v21, v228
	v_mul_f32_e32 v22, v22, v228
	v_mul_f32_e32 v23, v23, v228
	v_mul_f32_e32 v12, v12, v16
	v_mul_f32_e32 v13, v13, v17
	v_mul_f32_e32 v14, v14, v18
	v_mul_f32_e32 v15, v15, v19
	v_mul_f32_e32 v20, v20, v76
	v_mul_f32_e32 v21, v21, v77
	v_mul_f32_e32 v22, v22, v78
	v_mul_f32_e32 v23, v23, v79
	v_mul_f32_e32 v20, v20, v12
	v_mul_f32_e32 v21, v21, v13
	v_mul_f32_e32 v22, v22, v14
	v_mul_f32_e32 v23, v23, v15
	v_cvt_pk_bf16_f32 v20, v20, v21
	v_cvt_pk_bf16_f32 v21, v22, v23
	global_store_dwordx2 v204, v[20:21], s[30:31] offset:64
	s_waitcnt vmcnt(39)
	v_lshlrev_b32_e32 v12, 16, v30
	v_and_b32_e32 v13, 0xffff0000, v30
	v_lshlrev_b32_e32 v14, 16, v31
	v_and_b32_e32 v15, 0xffff0000, v31
	v_mul_f32_e32 v16, 0xbfb8aa3b, v12
	v_mul_f32_e32 v17, 0xbfb8aa3b, v13
	v_mul_f32_e32 v18, 0xbfb8aa3b, v14
	v_mul_f32_e32 v19, 0xbfb8aa3b, v15
	v_exp_f32_e32 v16, v16
	v_exp_f32_e32 v17, v17
	v_exp_f32_e32 v18, v18
	v_exp_f32_e32 v19, v19
	v_lshlrev_b32_e32 v20, 16, v106
	v_and_b32_e32 v21, 0xffff0000, v106
	v_lshlrev_b32_e32 v22, 16, v107
	v_and_b32_e32 v23, 0xffff0000, v107
	v_add_f32_e32 v16, 1.0, v16
	v_add_f32_e32 v17, 1.0, v17
	v_add_f32_e32 v18, 1.0, v18
	v_add_f32_e32 v19, 1.0, v19
	v_rcp_f32_e32 v16, v16
	v_rcp_f32_e32 v17, v17
	v_rcp_f32_e32 v18, v18
	v_rcp_f32_e32 v19, v19
	v_sub_f32_e32 v20, v20, v227
	v_sub_f32_e32 v21, v21, v227
	v_sub_f32_e32 v22, v22, v227
	v_sub_f32_e32 v23, v23, v227
	v_mul_f32_e32 v20, v20, v228
	v_mul_f32_e32 v21, v21, v228
	v_mul_f32_e32 v22, v22, v228
	v_mul_f32_e32 v23, v23, v228
	v_mul_f32_e32 v12, v12, v16
	v_mul_f32_e32 v13, v13, v17
	v_mul_f32_e32 v14, v14, v18
	v_mul_f32_e32 v15, v15, v19
	v_mul_f32_e32 v20, v20, v80
	v_mul_f32_e32 v21, v21, v81
	v_mul_f32_e32 v22, v22, v82
	v_mul_f32_e32 v23, v23, v83
	v_mul_f32_e32 v20, v20, v12
	v_mul_f32_e32 v21, v21, v13
	v_mul_f32_e32 v22, v22, v14
	v_mul_f32_e32 v23, v23, v15
	v_cvt_pk_bf16_f32 v20, v20, v21
	v_cvt_pk_bf16_f32 v21, v22, v23
	global_store_dwordx2 v204, v[20:21], s[30:31] offset:96
	s_waitcnt vmcnt(37)
	v_lshlrev_b32_e32 v12, 16, v32
	v_and_b32_e32 v13, 0xffff0000, v32
	v_lshlrev_b32_e32 v14, 16, v33
	v_and_b32_e32 v15, 0xffff0000, v33
	v_mul_f32_e32 v16, 0xbfb8aa3b, v12
	v_mul_f32_e32 v17, 0xbfb8aa3b, v13
	v_mul_f32_e32 v18, 0xbfb8aa3b, v14
	v_mul_f32_e32 v19, 0xbfb8aa3b, v15
	v_exp_f32_e32 v16, v16
	v_exp_f32_e32 v17, v17
	v_exp_f32_e32 v18, v18
	v_exp_f32_e32 v19, v19
	v_lshlrev_b32_e32 v20, 16, v108
	v_and_b32_e32 v21, 0xffff0000, v108
	v_lshlrev_b32_e32 v22, 16, v109
	v_and_b32_e32 v23, 0xffff0000, v109
	v_add_f32_e32 v16, 1.0, v16
	v_add_f32_e32 v17, 1.0, v17
	v_add_f32_e32 v18, 1.0, v18
	v_add_f32_e32 v19, 1.0, v19
	v_rcp_f32_e32 v16, v16
	v_rcp_f32_e32 v17, v17
	v_rcp_f32_e32 v18, v18
	v_rcp_f32_e32 v19, v19
	v_sub_f32_e32 v20, v20, v227
	v_sub_f32_e32 v21, v21, v227
	v_sub_f32_e32 v22, v22, v227
	v_sub_f32_e32 v23, v23, v227
	v_mul_f32_e32 v20, v20, v228
	v_mul_f32_e32 v21, v21, v228
	v_mul_f32_e32 v22, v22, v228
	v_mul_f32_e32 v23, v23, v228
	v_mul_f32_e32 v12, v12, v16
	v_mul_f32_e32 v13, v13, v17
	v_mul_f32_e32 v14, v14, v18
	v_mul_f32_e32 v15, v15, v19
	v_mul_f32_e32 v20, v20, v84
	v_mul_f32_e32 v21, v21, v85
	v_mul_f32_e32 v22, v22, v86
	v_mul_f32_e32 v23, v23, v87
	v_mul_f32_e32 v20, v20, v12
	v_mul_f32_e32 v21, v21, v13
	v_mul_f32_e32 v22, v22, v14
	v_mul_f32_e32 v23, v23, v15
	v_cvt_pk_bf16_f32 v20, v20, v21
	v_cvt_pk_bf16_f32 v21, v22, v23
	global_store_dwordx2 v204, v[20:21], s[30:31] offset:128
	s_waitcnt vmcnt(35)
	v_lshlrev_b32_e32 v12, 16, v34
	v_and_b32_e32 v13, 0xffff0000, v34
	v_lshlrev_b32_e32 v14, 16, v35
	v_and_b32_e32 v15, 0xffff0000, v35
	v_mul_f32_e32 v16, 0xbfb8aa3b, v12
	v_mul_f32_e32 v17, 0xbfb8aa3b, v13
	v_mul_f32_e32 v18, 0xbfb8aa3b, v14
	v_mul_f32_e32 v19, 0xbfb8aa3b, v15
	v_exp_f32_e32 v16, v16
	v_exp_f32_e32 v17, v17
	v_exp_f32_e32 v18, v18
	v_exp_f32_e32 v19, v19
	v_lshlrev_b32_e32 v20, 16, v110
	v_and_b32_e32 v21, 0xffff0000, v110
	v_lshlrev_b32_e32 v22, 16, v111
	v_and_b32_e32 v23, 0xffff0000, v111
	v_add_f32_e32 v16, 1.0, v16
	v_add_f32_e32 v17, 1.0, v17
	v_add_f32_e32 v18, 1.0, v18
	v_add_f32_e32 v19, 1.0, v19
	v_rcp_f32_e32 v16, v16
	v_rcp_f32_e32 v17, v17
	v_rcp_f32_e32 v18, v18
	v_rcp_f32_e32 v19, v19
	v_sub_f32_e32 v20, v20, v227
	v_sub_f32_e32 v21, v21, v227
	v_sub_f32_e32 v22, v22, v227
	v_sub_f32_e32 v23, v23, v227
	v_mul_f32_e32 v20, v20, v228
	v_mul_f32_e32 v21, v21, v228
	v_mul_f32_e32 v22, v22, v228
	v_mul_f32_e32 v23, v23, v228
	v_mul_f32_e32 v12, v12, v16
	v_mul_f32_e32 v13, v13, v17
	v_mul_f32_e32 v14, v14, v18
	v_mul_f32_e32 v15, v15, v19
	v_mul_f32_e32 v20, v20, v88
	v_mul_f32_e32 v21, v21, v89
	v_mul_f32_e32 v22, v22, v90
	v_mul_f32_e32 v23, v23, v91
	v_mul_f32_e32 v20, v20, v12
	v_mul_f32_e32 v21, v21, v13
	v_mul_f32_e32 v22, v22, v14
	v_mul_f32_e32 v23, v23, v15
	v_cvt_pk_bf16_f32 v20, v20, v21
	v_cvt_pk_bf16_f32 v21, v22, v23
	global_store_dwordx2 v204, v[20:21], s[30:31] offset:160
	s_waitcnt vmcnt(33)
	v_lshlrev_b32_e32 v12, 16, v36
	v_and_b32_e32 v13, 0xffff0000, v36
	v_lshlrev_b32_e32 v14, 16, v37
	v_and_b32_e32 v15, 0xffff0000, v37
	v_mul_f32_e32 v16, 0xbfb8aa3b, v12
	v_mul_f32_e32 v17, 0xbfb8aa3b, v13
	v_mul_f32_e32 v18, 0xbfb8aa3b, v14
	v_mul_f32_e32 v19, 0xbfb8aa3b, v15
	v_exp_f32_e32 v16, v16
	v_exp_f32_e32 v17, v17
	v_exp_f32_e32 v18, v18
	v_exp_f32_e32 v19, v19
	v_lshlrev_b32_e32 v20, 16, v112
	v_and_b32_e32 v21, 0xffff0000, v112
	v_lshlrev_b32_e32 v22, 16, v113
	v_and_b32_e32 v23, 0xffff0000, v113
	v_add_f32_e32 v16, 1.0, v16
	v_add_f32_e32 v17, 1.0, v17
	v_add_f32_e32 v18, 1.0, v18
	v_add_f32_e32 v19, 1.0, v19
	v_rcp_f32_e32 v16, v16
	v_rcp_f32_e32 v17, v17
	v_rcp_f32_e32 v18, v18
	v_rcp_f32_e32 v19, v19
	v_sub_f32_e32 v20, v20, v227
	v_sub_f32_e32 v21, v21, v227
	v_sub_f32_e32 v22, v22, v227
	v_sub_f32_e32 v23, v23, v227
	v_mul_f32_e32 v20, v20, v228
	v_mul_f32_e32 v21, v21, v228
	v_mul_f32_e32 v22, v22, v228
	v_mul_f32_e32 v23, v23, v228
	v_mul_f32_e32 v12, v12, v16
	v_mul_f32_e32 v13, v13, v17
	v_mul_f32_e32 v14, v14, v18
	v_mul_f32_e32 v15, v15, v19
	v_mul_f32_e32 v20, v20, v92
	v_mul_f32_e32 v21, v21, v93
	v_mul_f32_e32 v22, v22, v94
	v_mul_f32_e32 v23, v23, v95
	v_mul_f32_e32 v20, v20, v12
	v_mul_f32_e32 v21, v21, v13
	v_mul_f32_e32 v22, v22, v14
	v_mul_f32_e32 v23, v23, v15
	v_cvt_pk_bf16_f32 v20, v20, v21
	v_cvt_pk_bf16_f32 v21, v22, v23
	global_store_dwordx2 v204, v[20:21], s[30:31] offset:192
	s_waitcnt vmcnt(31)
	v_lshlrev_b32_e32 v12, 16, v38
	v_and_b32_e32 v13, 0xffff0000, v38
	v_lshlrev_b32_e32 v14, 16, v39
	v_and_b32_e32 v15, 0xffff0000, v39
	v_mul_f32_e32 v16, 0xbfb8aa3b, v12
	v_mul_f32_e32 v17, 0xbfb8aa3b, v13
	v_mul_f32_e32 v18, 0xbfb8aa3b, v14
	v_mul_f32_e32 v19, 0xbfb8aa3b, v15
	v_exp_f32_e32 v16, v16
	v_exp_f32_e32 v17, v17
	v_exp_f32_e32 v18, v18
	v_exp_f32_e32 v19, v19
	v_lshlrev_b32_e32 v20, 16, v114
	v_and_b32_e32 v21, 0xffff0000, v114
	v_lshlrev_b32_e32 v22, 16, v115
	v_and_b32_e32 v23, 0xffff0000, v115
	v_add_f32_e32 v16, 1.0, v16
	v_add_f32_e32 v17, 1.0, v17
	v_add_f32_e32 v18, 1.0, v18
	v_add_f32_e32 v19, 1.0, v19
	v_rcp_f32_e32 v16, v16
	v_rcp_f32_e32 v17, v17
	v_rcp_f32_e32 v18, v18
	v_rcp_f32_e32 v19, v19
	v_sub_f32_e32 v20, v20, v227
	v_sub_f32_e32 v21, v21, v227
	v_sub_f32_e32 v22, v22, v227
	v_sub_f32_e32 v23, v23, v227
	v_mul_f32_e32 v20, v20, v228
	v_mul_f32_e32 v21, v21, v228
	v_mul_f32_e32 v22, v22, v228
	v_mul_f32_e32 v23, v23, v228
	v_mul_f32_e32 v12, v12, v16
	v_mul_f32_e32 v13, v13, v17
	v_mul_f32_e32 v14, v14, v18
	v_mul_f32_e32 v15, v15, v19
	v_mul_f32_e32 v20, v20, v96
	v_mul_f32_e32 v21, v21, v97
	v_mul_f32_e32 v22, v22, v98
	v_mul_f32_e32 v23, v23, v99
	v_mul_f32_e32 v20, v20, v12
	v_mul_f32_e32 v21, v21, v13
	v_mul_f32_e32 v22, v22, v14
	v_mul_f32_e32 v23, v23, v15
	v_cvt_pk_bf16_f32 v20, v20, v21
	v_cvt_pk_bf16_f32 v21, v22, v23
	global_store_dwordx2 v204, v[20:21], s[30:31] offset:224
	global_load_dwordx2 v[24:25], v205, s[34:35] offset:512
	global_load_dwordx2 v[100:101], v204, s[30:31] offset:512
	global_load_dwordx4 v[68:71], v206, s[28:29] offset:1024
	global_load_dwordx2 v[26:27], v205, s[34:35] offset:544
	global_load_dwordx2 v[102:103], v204, s[30:31] offset:544
	global_load_dwordx4 v[72:75], v206, s[28:29] offset:1088
	global_load_dwordx2 v[28:29], v205, s[34:35] offset:576
	global_load_dwordx2 v[104:105], v204, s[30:31] offset:576
	global_load_dwordx4 v[76:79], v206, s[28:29] offset:1152
	global_load_dwordx2 v[30:31], v205, s[34:35] offset:608
	global_load_dwordx2 v[106:107], v204, s[30:31] offset:608
	global_load_dwordx4 v[80:83], v206, s[28:29] offset:1216
	global_load_dwordx2 v[32:33], v205, s[34:35] offset:640
	global_load_dwordx2 v[108:109], v204, s[30:31] offset:640
	global_load_dwordx4 v[84:87], v206, s[28:29] offset:1280
	global_load_dwordx2 v[34:35], v205, s[34:35] offset:672
	global_load_dwordx2 v[110:111], v204, s[30:31] offset:672
	global_load_dwordx4 v[88:91], v206, s[28:29] offset:1344
	global_load_dwordx2 v[36:37], v205, s[34:35] offset:704
	global_load_dwordx2 v[112:113], v204, s[30:31] offset:704
	global_load_dwordx4 v[92:95], v206, s[28:29] offset:1408
	global_load_dwordx2 v[38:39], v205, s[34:35] offset:736
	global_load_dwordx2 v[114:115], v204, s[30:31] offset:736
	global_load_dwordx4 v[96:99], v206, s[28:29] offset:1472
	s_waitcnt vmcnt(53)
	v_lshlrev_b32_e32 v12, 16, v40
	v_and_b32_e32 v13, 0xffff0000, v40
	v_lshlrev_b32_e32 v14, 16, v41
	v_and_b32_e32 v15, 0xffff0000, v41
	v_mul_f32_e32 v16, 0xbfb8aa3b, v12
	v_mul_f32_e32 v17, 0xbfb8aa3b, v13
	v_mul_f32_e32 v18, 0xbfb8aa3b, v14
	v_mul_f32_e32 v19, 0xbfb8aa3b, v15
	v_exp_f32_e32 v16, v16
	v_exp_f32_e32 v17, v17
	v_exp_f32_e32 v18, v18
	v_exp_f32_e32 v19, v19
	v_lshlrev_b32_e32 v20, 16, v116
	v_and_b32_e32 v21, 0xffff0000, v116
	v_lshlrev_b32_e32 v22, 16, v117
	v_and_b32_e32 v23, 0xffff0000, v117
	v_add_f32_e32 v16, 1.0, v16
	v_add_f32_e32 v17, 1.0, v17
	v_add_f32_e32 v18, 1.0, v18
	v_add_f32_e32 v19, 1.0, v19
	v_rcp_f32_e32 v16, v16
	v_rcp_f32_e32 v17, v17
	v_rcp_f32_e32 v18, v18
	v_rcp_f32_e32 v19, v19
	v_sub_f32_e32 v20, v20, v227
	v_sub_f32_e32 v21, v21, v227
	v_sub_f32_e32 v22, v22, v227
	v_sub_f32_e32 v23, v23, v227
	v_mul_f32_e32 v20, v20, v228
	v_mul_f32_e32 v21, v21, v228
	v_mul_f32_e32 v22, v22, v228
	v_mul_f32_e32 v23, v23, v228
	v_mul_f32_e32 v12, v12, v16
	v_mul_f32_e32 v13, v13, v17
	v_mul_f32_e32 v14, v14, v18
	v_mul_f32_e32 v15, v15, v19
	v_mul_f32_e32 v20, v20, v132
	v_mul_f32_e32 v21, v21, v133
	v_mul_f32_e32 v22, v22, v134
	v_mul_f32_e32 v23, v23, v135
	v_mul_f32_e32 v20, v20, v12
	v_mul_f32_e32 v21, v21, v13
	v_mul_f32_e32 v22, v22, v14
	v_mul_f32_e32 v23, v23, v15
	v_cvt_pk_bf16_f32 v20, v20, v21
	v_cvt_pk_bf16_f32 v21, v22, v23
	global_store_dwordx2 v204, v[20:21], s[30:31] offset:256
	s_waitcnt vmcnt(51)
	v_lshlrev_b32_e32 v12, 16, v42
	v_and_b32_e32 v13, 0xffff0000, v42
	v_lshlrev_b32_e32 v14, 16, v43
	v_and_b32_e32 v15, 0xffff0000, v43
	v_mul_f32_e32 v16, 0xbfb8aa3b, v12
	v_mul_f32_e32 v17, 0xbfb8aa3b, v13
	v_mul_f32_e32 v18, 0xbfb8aa3b, v14
	v_mul_f32_e32 v19, 0xbfb8aa3b, v15
	v_exp_f32_e32 v16, v16
	v_exp_f32_e32 v17, v17
	v_exp_f32_e32 v18, v18
	v_exp_f32_e32 v19, v19
	v_lshlrev_b32_e32 v20, 16, v118
	v_and_b32_e32 v21, 0xffff0000, v118
	v_lshlrev_b32_e32 v22, 16, v119
	v_and_b32_e32 v23, 0xffff0000, v119
	v_add_f32_e32 v16, 1.0, v16
	v_add_f32_e32 v17, 1.0, v17
	v_add_f32_e32 v18, 1.0, v18
	v_add_f32_e32 v19, 1.0, v19
	v_rcp_f32_e32 v16, v16
	v_rcp_f32_e32 v17, v17
	v_rcp_f32_e32 v18, v18
	v_rcp_f32_e32 v19, v19
	v_sub_f32_e32 v20, v20, v227
	v_sub_f32_e32 v21, v21, v227
	v_sub_f32_e32 v22, v22, v227
	v_sub_f32_e32 v23, v23, v227
	v_mul_f32_e32 v20, v20, v228
	v_mul_f32_e32 v21, v21, v228
	v_mul_f32_e32 v22, v22, v228
	v_mul_f32_e32 v23, v23, v228
	v_mul_f32_e32 v12, v12, v16
	v_mul_f32_e32 v13, v13, v17
	v_mul_f32_e32 v14, v14, v18
	v_mul_f32_e32 v15, v15, v19
	v_mul_f32_e32 v20, v20, v136
	v_mul_f32_e32 v21, v21, v137
	v_mul_f32_e32 v22, v22, v138
	v_mul_f32_e32 v23, v23, v139
	v_mul_f32_e32 v20, v20, v12
	v_mul_f32_e32 v21, v21, v13
	v_mul_f32_e32 v22, v22, v14
	v_mul_f32_e32 v23, v23, v15
	v_cvt_pk_bf16_f32 v20, v20, v21
	v_cvt_pk_bf16_f32 v21, v22, v23
	global_store_dwordx2 v204, v[20:21], s[30:31] offset:288
	s_waitcnt vmcnt(49)
	v_lshlrev_b32_e32 v12, 16, v44
	v_and_b32_e32 v13, 0xffff0000, v44
	v_lshlrev_b32_e32 v14, 16, v45
	v_and_b32_e32 v15, 0xffff0000, v45
	v_mul_f32_e32 v16, 0xbfb8aa3b, v12
	v_mul_f32_e32 v17, 0xbfb8aa3b, v13
	v_mul_f32_e32 v18, 0xbfb8aa3b, v14
	v_mul_f32_e32 v19, 0xbfb8aa3b, v15
	v_exp_f32_e32 v16, v16
	v_exp_f32_e32 v17, v17
	v_exp_f32_e32 v18, v18
	v_exp_f32_e32 v19, v19
	v_lshlrev_b32_e32 v20, 16, v120
	v_and_b32_e32 v21, 0xffff0000, v120
	v_lshlrev_b32_e32 v22, 16, v121
	v_and_b32_e32 v23, 0xffff0000, v121
	v_add_f32_e32 v16, 1.0, v16
	v_add_f32_e32 v17, 1.0, v17
	v_add_f32_e32 v18, 1.0, v18
	v_add_f32_e32 v19, 1.0, v19
	v_rcp_f32_e32 v16, v16
	v_rcp_f32_e32 v17, v17
	v_rcp_f32_e32 v18, v18
	v_rcp_f32_e32 v19, v19
	v_sub_f32_e32 v20, v20, v227
	v_sub_f32_e32 v21, v21, v227
	v_sub_f32_e32 v22, v22, v227
	v_sub_f32_e32 v23, v23, v227
	v_mul_f32_e32 v20, v20, v228
	v_mul_f32_e32 v21, v21, v228
	v_mul_f32_e32 v22, v22, v228
	v_mul_f32_e32 v23, v23, v228
	v_mul_f32_e32 v12, v12, v16
	v_mul_f32_e32 v13, v13, v17
	v_mul_f32_e32 v14, v14, v18
	v_mul_f32_e32 v15, v15, v19
	v_mul_f32_e32 v20, v20, v144
	v_mul_f32_e32 v21, v21, v145
	v_mul_f32_e32 v22, v22, v146
	v_mul_f32_e32 v23, v23, v147
	v_mul_f32_e32 v20, v20, v12
	v_mul_f32_e32 v21, v21, v13
	v_mul_f32_e32 v22, v22, v14
	v_mul_f32_e32 v23, v23, v15
	v_cvt_pk_bf16_f32 v20, v20, v21
	v_cvt_pk_bf16_f32 v21, v22, v23
	global_store_dwordx2 v204, v[20:21], s[30:31] offset:320
	s_waitcnt vmcnt(47)
	v_lshlrev_b32_e32 v12, 16, v46
	v_and_b32_e32 v13, 0xffff0000, v46
	v_lshlrev_b32_e32 v14, 16, v47
	v_and_b32_e32 v15, 0xffff0000, v47
	v_mul_f32_e32 v16, 0xbfb8aa3b, v12
	v_mul_f32_e32 v17, 0xbfb8aa3b, v13
	v_mul_f32_e32 v18, 0xbfb8aa3b, v14
	v_mul_f32_e32 v19, 0xbfb8aa3b, v15
	v_exp_f32_e32 v16, v16
	v_exp_f32_e32 v17, v17
	v_exp_f32_e32 v18, v18
	v_exp_f32_e32 v19, v19
	v_lshlrev_b32_e32 v20, 16, v122
	v_and_b32_e32 v21, 0xffff0000, v122
	v_lshlrev_b32_e32 v22, 16, v123
	v_and_b32_e32 v23, 0xffff0000, v123
	v_add_f32_e32 v16, 1.0, v16
	v_add_f32_e32 v17, 1.0, v17
	v_add_f32_e32 v18, 1.0, v18
	v_add_f32_e32 v19, 1.0, v19
	v_rcp_f32_e32 v16, v16
	v_rcp_f32_e32 v17, v17
	v_rcp_f32_e32 v18, v18
	v_rcp_f32_e32 v19, v19
	v_sub_f32_e32 v20, v20, v227
	v_sub_f32_e32 v21, v21, v227
	v_sub_f32_e32 v22, v22, v227
	v_sub_f32_e32 v23, v23, v227
	v_mul_f32_e32 v20, v20, v228
	v_mul_f32_e32 v21, v21, v228
	v_mul_f32_e32 v22, v22, v228
	v_mul_f32_e32 v23, v23, v228
	v_mul_f32_e32 v12, v12, v16
	v_mul_f32_e32 v13, v13, v17
	v_mul_f32_e32 v14, v14, v18
	v_mul_f32_e32 v15, v15, v19
	v_mul_f32_e32 v20, v20, v148
	v_mul_f32_e32 v21, v21, v149
	v_mul_f32_e32 v22, v22, v150
	v_mul_f32_e32 v23, v23, v151
	v_mul_f32_e32 v20, v20, v12
	v_mul_f32_e32 v21, v21, v13
	v_mul_f32_e32 v22, v22, v14
	v_mul_f32_e32 v23, v23, v15
	v_cvt_pk_bf16_f32 v20, v20, v21
	v_cvt_pk_bf16_f32 v21, v22, v23
	global_store_dwordx2 v204, v[20:21], s[30:31] offset:352
	s_waitcnt vmcnt(45)
	v_lshlrev_b32_e32 v12, 16, v48
	v_and_b32_e32 v13, 0xffff0000, v48
	v_lshlrev_b32_e32 v14, 16, v49
	v_and_b32_e32 v15, 0xffff0000, v49
	v_mul_f32_e32 v16, 0xbfb8aa3b, v12
	v_mul_f32_e32 v17, 0xbfb8aa3b, v13
	v_mul_f32_e32 v18, 0xbfb8aa3b, v14
	v_mul_f32_e32 v19, 0xbfb8aa3b, v15
	v_exp_f32_e32 v16, v16
	v_exp_f32_e32 v17, v17
	v_exp_f32_e32 v18, v18
	v_exp_f32_e32 v19, v19
	v_lshlrev_b32_e32 v20, 16, v124
	v_and_b32_e32 v21, 0xffff0000, v124
	v_lshlrev_b32_e32 v22, 16, v125
	v_and_b32_e32 v23, 0xffff0000, v125
	v_add_f32_e32 v16, 1.0, v16
	v_add_f32_e32 v17, 1.0, v17
	v_add_f32_e32 v18, 1.0, v18
	v_add_f32_e32 v19, 1.0, v19
	v_rcp_f32_e32 v16, v16
	v_rcp_f32_e32 v17, v17
	v_rcp_f32_e32 v18, v18
	v_rcp_f32_e32 v19, v19
	v_sub_f32_e32 v20, v20, v227
	v_sub_f32_e32 v21, v21, v227
	v_sub_f32_e32 v22, v22, v227
	v_sub_f32_e32 v23, v23, v227
	v_mul_f32_e32 v20, v20, v228
	v_mul_f32_e32 v21, v21, v228
	v_mul_f32_e32 v22, v22, v228
	v_mul_f32_e32 v23, v23, v228
	v_mul_f32_e32 v12, v12, v16
	v_mul_f32_e32 v13, v13, v17
	v_mul_f32_e32 v14, v14, v18
	v_mul_f32_e32 v15, v15, v19
	v_mul_f32_e32 v20, v20, v152
	v_mul_f32_e32 v21, v21, v153
	v_mul_f32_e32 v22, v22, v154
	v_mul_f32_e32 v23, v23, v155
	v_mul_f32_e32 v20, v20, v12
	v_mul_f32_e32 v21, v21, v13
	v_mul_f32_e32 v22, v22, v14
	v_mul_f32_e32 v23, v23, v15
	v_cvt_pk_bf16_f32 v20, v20, v21
	v_cvt_pk_bf16_f32 v21, v22, v23
	global_store_dwordx2 v204, v[20:21], s[30:31] offset:384
	s_waitcnt vmcnt(43)
	v_lshlrev_b32_e32 v12, 16, v50
	v_and_b32_e32 v13, 0xffff0000, v50
	v_lshlrev_b32_e32 v14, 16, v51
	v_and_b32_e32 v15, 0xffff0000, v51
	v_mul_f32_e32 v16, 0xbfb8aa3b, v12
	v_mul_f32_e32 v17, 0xbfb8aa3b, v13
	v_mul_f32_e32 v18, 0xbfb8aa3b, v14
	v_mul_f32_e32 v19, 0xbfb8aa3b, v15
	v_exp_f32_e32 v16, v16
	v_exp_f32_e32 v17, v17
	v_exp_f32_e32 v18, v18
	v_exp_f32_e32 v19, v19
	v_lshlrev_b32_e32 v20, 16, v126
	v_and_b32_e32 v21, 0xffff0000, v126
	v_lshlrev_b32_e32 v22, 16, v127
	v_and_b32_e32 v23, 0xffff0000, v127
	v_add_f32_e32 v16, 1.0, v16
	v_add_f32_e32 v17, 1.0, v17
	v_add_f32_e32 v18, 1.0, v18
	v_add_f32_e32 v19, 1.0, v19
	v_rcp_f32_e32 v16, v16
	v_rcp_f32_e32 v17, v17
	v_rcp_f32_e32 v18, v18
	v_rcp_f32_e32 v19, v19
	v_sub_f32_e32 v20, v20, v227
	v_sub_f32_e32 v21, v21, v227
	v_sub_f32_e32 v22, v22, v227
	v_sub_f32_e32 v23, v23, v227
	v_mul_f32_e32 v20, v20, v228
	v_mul_f32_e32 v21, v21, v228
	v_mul_f32_e32 v22, v22, v228
	v_mul_f32_e32 v23, v23, v228
	v_mul_f32_e32 v12, v12, v16
	v_mul_f32_e32 v13, v13, v17
	v_mul_f32_e32 v14, v14, v18
	v_mul_f32_e32 v15, v15, v19
	v_mul_f32_e32 v20, v20, v156
	v_mul_f32_e32 v21, v21, v157
	v_mul_f32_e32 v22, v22, v158
	v_mul_f32_e32 v23, v23, v159
	v_mul_f32_e32 v20, v20, v12
	v_mul_f32_e32 v21, v21, v13
	v_mul_f32_e32 v22, v22, v14
	v_mul_f32_e32 v23, v23, v15
	v_cvt_pk_bf16_f32 v20, v20, v21
	v_cvt_pk_bf16_f32 v21, v22, v23
	global_store_dwordx2 v204, v[20:21], s[30:31] offset:416
	s_waitcnt vmcnt(41)
	v_lshlrev_b32_e32 v12, 16, v52
	v_and_b32_e32 v13, 0xffff0000, v52
	v_lshlrev_b32_e32 v14, 16, v53
	v_and_b32_e32 v15, 0xffff0000, v53
	v_mul_f32_e32 v16, 0xbfb8aa3b, v12
	v_mul_f32_e32 v17, 0xbfb8aa3b, v13
	v_mul_f32_e32 v18, 0xbfb8aa3b, v14
	v_mul_f32_e32 v19, 0xbfb8aa3b, v15
	v_exp_f32_e32 v16, v16
	v_exp_f32_e32 v17, v17
	v_exp_f32_e32 v18, v18
	v_exp_f32_e32 v19, v19
	v_lshlrev_b32_e32 v20, 16, v128
	v_and_b32_e32 v21, 0xffff0000, v128
	v_lshlrev_b32_e32 v22, 16, v129
	v_and_b32_e32 v23, 0xffff0000, v129
	v_add_f32_e32 v16, 1.0, v16
	v_add_f32_e32 v17, 1.0, v17
	v_add_f32_e32 v18, 1.0, v18
	v_add_f32_e32 v19, 1.0, v19
	v_rcp_f32_e32 v16, v16
	v_rcp_f32_e32 v17, v17
	v_rcp_f32_e32 v18, v18
	v_rcp_f32_e32 v19, v19
	v_sub_f32_e32 v20, v20, v227
	v_sub_f32_e32 v21, v21, v227
	v_sub_f32_e32 v22, v22, v227
	v_sub_f32_e32 v23, v23, v227
	v_mul_f32_e32 v20, v20, v228
	v_mul_f32_e32 v21, v21, v228
	v_mul_f32_e32 v22, v22, v228
	v_mul_f32_e32 v23, v23, v228
	v_mul_f32_e32 v12, v12, v16
	v_mul_f32_e32 v13, v13, v17
	v_mul_f32_e32 v14, v14, v18
	v_mul_f32_e32 v15, v15, v19
	v_mul_f32_e32 v20, v20, v160
	v_mul_f32_e32 v21, v21, v161
	v_mul_f32_e32 v22, v22, v162
	v_mul_f32_e32 v23, v23, v163
	v_mul_f32_e32 v20, v20, v12
	v_mul_f32_e32 v21, v21, v13
	v_mul_f32_e32 v22, v22, v14
	v_mul_f32_e32 v23, v23, v15
	v_cvt_pk_bf16_f32 v20, v20, v21
	v_cvt_pk_bf16_f32 v21, v22, v23
	global_store_dwordx2 v204, v[20:21], s[30:31] offset:448
	s_waitcnt vmcnt(39)
	v_lshlrev_b32_e32 v12, 16, v54
	v_and_b32_e32 v13, 0xffff0000, v54
	v_lshlrev_b32_e32 v14, 16, v55
	v_and_b32_e32 v15, 0xffff0000, v55
	v_mul_f32_e32 v16, 0xbfb8aa3b, v12
	v_mul_f32_e32 v17, 0xbfb8aa3b, v13
	v_mul_f32_e32 v18, 0xbfb8aa3b, v14
	v_mul_f32_e32 v19, 0xbfb8aa3b, v15
	v_exp_f32_e32 v16, v16
	v_exp_f32_e32 v17, v17
	v_exp_f32_e32 v18, v18
	v_exp_f32_e32 v19, v19
	v_lshlrev_b32_e32 v20, 16, v130
	v_and_b32_e32 v21, 0xffff0000, v130
	v_lshlrev_b32_e32 v22, 16, v131
	v_and_b32_e32 v23, 0xffff0000, v131
	v_add_f32_e32 v16, 1.0, v16
	v_add_f32_e32 v17, 1.0, v17
	v_add_f32_e32 v18, 1.0, v18
	v_add_f32_e32 v19, 1.0, v19
	v_rcp_f32_e32 v16, v16
	v_rcp_f32_e32 v17, v17
	v_rcp_f32_e32 v18, v18
	v_rcp_f32_e32 v19, v19
	v_sub_f32_e32 v20, v20, v227
	v_sub_f32_e32 v21, v21, v227
	v_sub_f32_e32 v22, v22, v227
	v_sub_f32_e32 v23, v23, v227
	v_mul_f32_e32 v20, v20, v228
	v_mul_f32_e32 v21, v21, v228
	v_mul_f32_e32 v22, v22, v228
	v_mul_f32_e32 v23, v23, v228
	v_mul_f32_e32 v12, v12, v16
	v_mul_f32_e32 v13, v13, v17
	v_mul_f32_e32 v14, v14, v18
	v_mul_f32_e32 v15, v15, v19
	v_mul_f32_e32 v20, v20, v164
	v_mul_f32_e32 v21, v21, v165
	v_mul_f32_e32 v22, v22, v166
	v_mul_f32_e32 v23, v23, v167
	v_mul_f32_e32 v20, v20, v12
	v_mul_f32_e32 v21, v21, v13
	v_mul_f32_e32 v22, v22, v14
	v_mul_f32_e32 v23, v23, v15
	v_cvt_pk_bf16_f32 v20, v20, v21
	v_cvt_pk_bf16_f32 v21, v22, v23
	global_store_dwordx2 v204, v[20:21], s[30:31] offset:480
	global_load_dwordx2 v[40:41], v205, s[34:35] offset:768
	global_load_dwordx2 v[116:117], v204, s[30:31] offset:768
	global_load_dwordx4 v[132:135], v206, s[28:29] offset:1536
	global_load_dwordx2 v[42:43], v205, s[34:35] offset:800
	global_load_dwordx2 v[118:119], v204, s[30:31] offset:800
	global_load_dwordx4 v[136:139], v206, s[28:29] offset:1600
	global_load_dwordx2 v[44:45], v205, s[34:35] offset:832
	global_load_dwordx2 v[120:121], v204, s[30:31] offset:832
	global_load_dwordx4 v[144:147], v206, s[28:29] offset:1664
	global_load_dwordx2 v[46:47], v205, s[34:35] offset:864
	global_load_dwordx2 v[122:123], v204, s[30:31] offset:864
	global_load_dwordx4 v[148:151], v206, s[28:29] offset:1728
	global_load_dwordx2 v[48:49], v205, s[34:35] offset:896
	global_load_dwordx2 v[124:125], v204, s[30:31] offset:896
	global_load_dwordx4 v[152:155], v206, s[28:29] offset:1792
	global_load_dwordx2 v[50:51], v205, s[34:35] offset:928
	global_load_dwordx2 v[126:127], v204, s[30:31] offset:928
	global_load_dwordx4 v[156:159], v206, s[28:29] offset:1856
	global_load_dwordx2 v[52:53], v205, s[34:35] offset:960
	global_load_dwordx2 v[128:129], v204, s[30:31] offset:960
	global_load_dwordx4 v[160:163], v206, s[28:29] offset:1920
	global_load_dwordx2 v[54:55], v205, s[34:35] offset:992
	global_load_dwordx2 v[130:131], v204, s[30:31] offset:992
	global_load_dwordx4 v[164:167], v206, s[28:29] offset:1984
	s_waitcnt vmcnt(53)
	v_lshlrev_b32_e32 v12, 16, v24
	v_and_b32_e32 v13, 0xffff0000, v24
	v_lshlrev_b32_e32 v14, 16, v25
	v_and_b32_e32 v15, 0xffff0000, v25
	v_mul_f32_e32 v16, 0xbfb8aa3b, v12
	v_mul_f32_e32 v17, 0xbfb8aa3b, v13
	v_mul_f32_e32 v18, 0xbfb8aa3b, v14
	v_mul_f32_e32 v19, 0xbfb8aa3b, v15
	v_exp_f32_e32 v16, v16
	v_exp_f32_e32 v17, v17
	v_exp_f32_e32 v18, v18
	v_exp_f32_e32 v19, v19
	v_lshlrev_b32_e32 v20, 16, v100
	v_and_b32_e32 v21, 0xffff0000, v100
	v_lshlrev_b32_e32 v22, 16, v101
	v_and_b32_e32 v23, 0xffff0000, v101
	v_add_f32_e32 v16, 1.0, v16
	v_add_f32_e32 v17, 1.0, v17
	v_add_f32_e32 v18, 1.0, v18
	v_add_f32_e32 v19, 1.0, v19
	v_rcp_f32_e32 v16, v16
	v_rcp_f32_e32 v17, v17
	v_rcp_f32_e32 v18, v18
	v_rcp_f32_e32 v19, v19
	v_sub_f32_e32 v20, v20, v227
	v_sub_f32_e32 v21, v21, v227
	v_sub_f32_e32 v22, v22, v227
	v_sub_f32_e32 v23, v23, v227
	v_mul_f32_e32 v20, v20, v228
	v_mul_f32_e32 v21, v21, v228
	v_mul_f32_e32 v22, v22, v228
	v_mul_f32_e32 v23, v23, v228
	v_mul_f32_e32 v12, v12, v16
	v_mul_f32_e32 v13, v13, v17
	v_mul_f32_e32 v14, v14, v18
	v_mul_f32_e32 v15, v15, v19
	v_mul_f32_e32 v20, v20, v68
	v_mul_f32_e32 v21, v21, v69
	v_mul_f32_e32 v22, v22, v70
	v_mul_f32_e32 v23, v23, v71
	v_mul_f32_e32 v20, v20, v12
	v_mul_f32_e32 v21, v21, v13
	v_mul_f32_e32 v22, v22, v14
	v_mul_f32_e32 v23, v23, v15
	v_cvt_pk_bf16_f32 v20, v20, v21
	v_cvt_pk_bf16_f32 v21, v22, v23
	global_store_dwordx2 v204, v[20:21], s[30:31] offset:512
	s_waitcnt vmcnt(51)
	v_lshlrev_b32_e32 v12, 16, v26
	v_and_b32_e32 v13, 0xffff0000, v26
	v_lshlrev_b32_e32 v14, 16, v27
	v_and_b32_e32 v15, 0xffff0000, v27
	v_mul_f32_e32 v16, 0xbfb8aa3b, v12
	v_mul_f32_e32 v17, 0xbfb8aa3b, v13
	v_mul_f32_e32 v18, 0xbfb8aa3b, v14
	v_mul_f32_e32 v19, 0xbfb8aa3b, v15
	v_exp_f32_e32 v16, v16
	v_exp_f32_e32 v17, v17
	v_exp_f32_e32 v18, v18
	v_exp_f32_e32 v19, v19
	v_lshlrev_b32_e32 v20, 16, v102
	v_and_b32_e32 v21, 0xffff0000, v102
	v_lshlrev_b32_e32 v22, 16, v103
	v_and_b32_e32 v23, 0xffff0000, v103
	v_add_f32_e32 v16, 1.0, v16
	v_add_f32_e32 v17, 1.0, v17
	v_add_f32_e32 v18, 1.0, v18
	v_add_f32_e32 v19, 1.0, v19
	v_rcp_f32_e32 v16, v16
	v_rcp_f32_e32 v17, v17
	v_rcp_f32_e32 v18, v18
	v_rcp_f32_e32 v19, v19
	v_sub_f32_e32 v20, v20, v227
	v_sub_f32_e32 v21, v21, v227
	v_sub_f32_e32 v22, v22, v227
	v_sub_f32_e32 v23, v23, v227
	v_mul_f32_e32 v20, v20, v228
	v_mul_f32_e32 v21, v21, v228
	v_mul_f32_e32 v22, v22, v228
	v_mul_f32_e32 v23, v23, v228
	v_mul_f32_e32 v12, v12, v16
	v_mul_f32_e32 v13, v13, v17
	v_mul_f32_e32 v14, v14, v18
	v_mul_f32_e32 v15, v15, v19
	v_mul_f32_e32 v20, v20, v72
	v_mul_f32_e32 v21, v21, v73
	v_mul_f32_e32 v22, v22, v74
	v_mul_f32_e32 v23, v23, v75
	v_mul_f32_e32 v20, v20, v12
	v_mul_f32_e32 v21, v21, v13
	v_mul_f32_e32 v22, v22, v14
	v_mul_f32_e32 v23, v23, v15
	v_cvt_pk_bf16_f32 v20, v20, v21
	v_cvt_pk_bf16_f32 v21, v22, v23
	global_store_dwordx2 v204, v[20:21], s[30:31] offset:544
	s_waitcnt vmcnt(49)
	v_lshlrev_b32_e32 v12, 16, v28
	v_and_b32_e32 v13, 0xffff0000, v28
	v_lshlrev_b32_e32 v14, 16, v29
	v_and_b32_e32 v15, 0xffff0000, v29
	v_mul_f32_e32 v16, 0xbfb8aa3b, v12
	v_mul_f32_e32 v17, 0xbfb8aa3b, v13
	v_mul_f32_e32 v18, 0xbfb8aa3b, v14
	v_mul_f32_e32 v19, 0xbfb8aa3b, v15
	v_exp_f32_e32 v16, v16
	v_exp_f32_e32 v17, v17
	v_exp_f32_e32 v18, v18
	v_exp_f32_e32 v19, v19
	v_lshlrev_b32_e32 v20, 16, v104
	v_and_b32_e32 v21, 0xffff0000, v104
	v_lshlrev_b32_e32 v22, 16, v105
	v_and_b32_e32 v23, 0xffff0000, v105
	v_add_f32_e32 v16, 1.0, v16
	v_add_f32_e32 v17, 1.0, v17
	v_add_f32_e32 v18, 1.0, v18
	v_add_f32_e32 v19, 1.0, v19
	v_rcp_f32_e32 v16, v16
	v_rcp_f32_e32 v17, v17
	v_rcp_f32_e32 v18, v18
	v_rcp_f32_e32 v19, v19
	v_sub_f32_e32 v20, v20, v227
	v_sub_f32_e32 v21, v21, v227
	v_sub_f32_e32 v22, v22, v227
	v_sub_f32_e32 v23, v23, v227
	v_mul_f32_e32 v20, v20, v228
	v_mul_f32_e32 v21, v21, v228
	v_mul_f32_e32 v22, v22, v228
	v_mul_f32_e32 v23, v23, v228
	v_mul_f32_e32 v12, v12, v16
	v_mul_f32_e32 v13, v13, v17
	v_mul_f32_e32 v14, v14, v18
	v_mul_f32_e32 v15, v15, v19
	v_mul_f32_e32 v20, v20, v76
	v_mul_f32_e32 v21, v21, v77
	v_mul_f32_e32 v22, v22, v78
	v_mul_f32_e32 v23, v23, v79
	v_mul_f32_e32 v20, v20, v12
	v_mul_f32_e32 v21, v21, v13
	v_mul_f32_e32 v22, v22, v14
	v_mul_f32_e32 v23, v23, v15
	v_cvt_pk_bf16_f32 v20, v20, v21
	v_cvt_pk_bf16_f32 v21, v22, v23
	global_store_dwordx2 v204, v[20:21], s[30:31] offset:576
	s_waitcnt vmcnt(47)
	v_lshlrev_b32_e32 v12, 16, v30
	v_and_b32_e32 v13, 0xffff0000, v30
	v_lshlrev_b32_e32 v14, 16, v31
	v_and_b32_e32 v15, 0xffff0000, v31
	v_mul_f32_e32 v16, 0xbfb8aa3b, v12
	v_mul_f32_e32 v17, 0xbfb8aa3b, v13
	v_mul_f32_e32 v18, 0xbfb8aa3b, v14
	v_mul_f32_e32 v19, 0xbfb8aa3b, v15
	v_exp_f32_e32 v16, v16
	v_exp_f32_e32 v17, v17
	v_exp_f32_e32 v18, v18
	v_exp_f32_e32 v19, v19
	v_lshlrev_b32_e32 v20, 16, v106
	v_and_b32_e32 v21, 0xffff0000, v106
	v_lshlrev_b32_e32 v22, 16, v107
	v_and_b32_e32 v23, 0xffff0000, v107
	v_add_f32_e32 v16, 1.0, v16
	v_add_f32_e32 v17, 1.0, v17
	v_add_f32_e32 v18, 1.0, v18
	v_add_f32_e32 v19, 1.0, v19
	v_rcp_f32_e32 v16, v16
	v_rcp_f32_e32 v17, v17
	v_rcp_f32_e32 v18, v18
	v_rcp_f32_e32 v19, v19
	v_sub_f32_e32 v20, v20, v227
	v_sub_f32_e32 v21, v21, v227
	v_sub_f32_e32 v22, v22, v227
	v_sub_f32_e32 v23, v23, v227
	v_mul_f32_e32 v20, v20, v228
	v_mul_f32_e32 v21, v21, v228
	v_mul_f32_e32 v22, v22, v228
	v_mul_f32_e32 v23, v23, v228
	v_mul_f32_e32 v12, v12, v16
	v_mul_f32_e32 v13, v13, v17
	v_mul_f32_e32 v14, v14, v18
	v_mul_f32_e32 v15, v15, v19
	v_mul_f32_e32 v20, v20, v80
	v_mul_f32_e32 v21, v21, v81
	v_mul_f32_e32 v22, v22, v82
	v_mul_f32_e32 v23, v23, v83
	v_mul_f32_e32 v20, v20, v12
	v_mul_f32_e32 v21, v21, v13
	v_mul_f32_e32 v22, v22, v14
	v_mul_f32_e32 v23, v23, v15
	v_cvt_pk_bf16_f32 v20, v20, v21
	v_cvt_pk_bf16_f32 v21, v22, v23
	global_store_dwordx2 v204, v[20:21], s[30:31] offset:608
	s_waitcnt vmcnt(45)
	v_lshlrev_b32_e32 v12, 16, v32
	v_and_b32_e32 v13, 0xffff0000, v32
	v_lshlrev_b32_e32 v14, 16, v33
	v_and_b32_e32 v15, 0xffff0000, v33
	v_mul_f32_e32 v16, 0xbfb8aa3b, v12
	v_mul_f32_e32 v17, 0xbfb8aa3b, v13
	v_mul_f32_e32 v18, 0xbfb8aa3b, v14
	v_mul_f32_e32 v19, 0xbfb8aa3b, v15
	v_exp_f32_e32 v16, v16
	v_exp_f32_e32 v17, v17
	v_exp_f32_e32 v18, v18
	v_exp_f32_e32 v19, v19
	v_lshlrev_b32_e32 v20, 16, v108
	v_and_b32_e32 v21, 0xffff0000, v108
	v_lshlrev_b32_e32 v22, 16, v109
	v_and_b32_e32 v23, 0xffff0000, v109
	v_add_f32_e32 v16, 1.0, v16
	v_add_f32_e32 v17, 1.0, v17
	v_add_f32_e32 v18, 1.0, v18
	v_add_f32_e32 v19, 1.0, v19
	v_rcp_f32_e32 v16, v16
	v_rcp_f32_e32 v17, v17
	v_rcp_f32_e32 v18, v18
	v_rcp_f32_e32 v19, v19
	v_sub_f32_e32 v20, v20, v227
	v_sub_f32_e32 v21, v21, v227
	v_sub_f32_e32 v22, v22, v227
	v_sub_f32_e32 v23, v23, v227
	v_mul_f32_e32 v20, v20, v228
	v_mul_f32_e32 v21, v21, v228
	v_mul_f32_e32 v22, v22, v228
	v_mul_f32_e32 v23, v23, v228
	v_mul_f32_e32 v12, v12, v16
	v_mul_f32_e32 v13, v13, v17
	v_mul_f32_e32 v14, v14, v18
	v_mul_f32_e32 v15, v15, v19
	v_mul_f32_e32 v20, v20, v84
	v_mul_f32_e32 v21, v21, v85
	v_mul_f32_e32 v22, v22, v86
	v_mul_f32_e32 v23, v23, v87
	v_mul_f32_e32 v20, v20, v12
	v_mul_f32_e32 v21, v21, v13
	v_mul_f32_e32 v22, v22, v14
	v_mul_f32_e32 v23, v23, v15
	v_cvt_pk_bf16_f32 v20, v20, v21
	v_cvt_pk_bf16_f32 v21, v22, v23
	global_store_dwordx2 v204, v[20:21], s[30:31] offset:640
	s_waitcnt vmcnt(43)
	v_lshlrev_b32_e32 v12, 16, v34
	v_and_b32_e32 v13, 0xffff0000, v34
	v_lshlrev_b32_e32 v14, 16, v35
	v_and_b32_e32 v15, 0xffff0000, v35
	v_mul_f32_e32 v16, 0xbfb8aa3b, v12
	v_mul_f32_e32 v17, 0xbfb8aa3b, v13
	v_mul_f32_e32 v18, 0xbfb8aa3b, v14
	v_mul_f32_e32 v19, 0xbfb8aa3b, v15
	v_exp_f32_e32 v16, v16
	v_exp_f32_e32 v17, v17
	v_exp_f32_e32 v18, v18
	v_exp_f32_e32 v19, v19
	v_lshlrev_b32_e32 v20, 16, v110
	v_and_b32_e32 v21, 0xffff0000, v110
	v_lshlrev_b32_e32 v22, 16, v111
	v_and_b32_e32 v23, 0xffff0000, v111
	v_add_f32_e32 v16, 1.0, v16
	v_add_f32_e32 v17, 1.0, v17
	v_add_f32_e32 v18, 1.0, v18
	v_add_f32_e32 v19, 1.0, v19
	v_rcp_f32_e32 v16, v16
	v_rcp_f32_e32 v17, v17
	v_rcp_f32_e32 v18, v18
	v_rcp_f32_e32 v19, v19
	v_sub_f32_e32 v20, v20, v227
	v_sub_f32_e32 v21, v21, v227
	v_sub_f32_e32 v22, v22, v227
	v_sub_f32_e32 v23, v23, v227
	v_mul_f32_e32 v20, v20, v228
	v_mul_f32_e32 v21, v21, v228
	v_mul_f32_e32 v22, v22, v228
	v_mul_f32_e32 v23, v23, v228
	v_mul_f32_e32 v12, v12, v16
	v_mul_f32_e32 v13, v13, v17
	v_mul_f32_e32 v14, v14, v18
	v_mul_f32_e32 v15, v15, v19
	v_mul_f32_e32 v20, v20, v88
	v_mul_f32_e32 v21, v21, v89
	v_mul_f32_e32 v22, v22, v90
	v_mul_f32_e32 v23, v23, v91
	v_mul_f32_e32 v20, v20, v12
	v_mul_f32_e32 v21, v21, v13
	v_mul_f32_e32 v22, v22, v14
	v_mul_f32_e32 v23, v23, v15
	v_cvt_pk_bf16_f32 v20, v20, v21
	v_cvt_pk_bf16_f32 v21, v22, v23
	global_store_dwordx2 v204, v[20:21], s[30:31] offset:672
	s_waitcnt vmcnt(41)
	v_lshlrev_b32_e32 v12, 16, v36
	v_and_b32_e32 v13, 0xffff0000, v36
	v_lshlrev_b32_e32 v14, 16, v37
	v_and_b32_e32 v15, 0xffff0000, v37
	v_mul_f32_e32 v16, 0xbfb8aa3b, v12
	v_mul_f32_e32 v17, 0xbfb8aa3b, v13
	v_mul_f32_e32 v18, 0xbfb8aa3b, v14
	v_mul_f32_e32 v19, 0xbfb8aa3b, v15
	v_exp_f32_e32 v16, v16
	v_exp_f32_e32 v17, v17
	v_exp_f32_e32 v18, v18
	v_exp_f32_e32 v19, v19
	v_lshlrev_b32_e32 v20, 16, v112
	v_and_b32_e32 v21, 0xffff0000, v112
	v_lshlrev_b32_e32 v22, 16, v113
	v_and_b32_e32 v23, 0xffff0000, v113
	v_add_f32_e32 v16, 1.0, v16
	v_add_f32_e32 v17, 1.0, v17
	v_add_f32_e32 v18, 1.0, v18
	v_add_f32_e32 v19, 1.0, v19
	v_rcp_f32_e32 v16, v16
	v_rcp_f32_e32 v17, v17
	v_rcp_f32_e32 v18, v18
	v_rcp_f32_e32 v19, v19
	v_sub_f32_e32 v20, v20, v227
	v_sub_f32_e32 v21, v21, v227
	v_sub_f32_e32 v22, v22, v227
	v_sub_f32_e32 v23, v23, v227
	v_mul_f32_e32 v20, v20, v228
	v_mul_f32_e32 v21, v21, v228
	v_mul_f32_e32 v22, v22, v228
	v_mul_f32_e32 v23, v23, v228
	v_mul_f32_e32 v12, v12, v16
	v_mul_f32_e32 v13, v13, v17
	v_mul_f32_e32 v14, v14, v18
	v_mul_f32_e32 v15, v15, v19
	v_mul_f32_e32 v20, v20, v92
	v_mul_f32_e32 v21, v21, v93
	v_mul_f32_e32 v22, v22, v94
	v_mul_f32_e32 v23, v23, v95
	v_mul_f32_e32 v20, v20, v12
	v_mul_f32_e32 v21, v21, v13
	v_mul_f32_e32 v22, v22, v14
	v_mul_f32_e32 v23, v23, v15
	v_cvt_pk_bf16_f32 v20, v20, v21
	v_cvt_pk_bf16_f32 v21, v22, v23
	global_store_dwordx2 v204, v[20:21], s[30:31] offset:704
	s_waitcnt vmcnt(39)
	v_lshlrev_b32_e32 v12, 16, v38
	v_and_b32_e32 v13, 0xffff0000, v38
	v_lshlrev_b32_e32 v14, 16, v39
	v_and_b32_e32 v15, 0xffff0000, v39
	v_mul_f32_e32 v16, 0xbfb8aa3b, v12
	v_mul_f32_e32 v17, 0xbfb8aa3b, v13
	v_mul_f32_e32 v18, 0xbfb8aa3b, v14
	v_mul_f32_e32 v19, 0xbfb8aa3b, v15
	v_exp_f32_e32 v16, v16
	v_exp_f32_e32 v17, v17
	v_exp_f32_e32 v18, v18
	v_exp_f32_e32 v19, v19
	v_lshlrev_b32_e32 v20, 16, v114
	v_and_b32_e32 v21, 0xffff0000, v114
	v_lshlrev_b32_e32 v22, 16, v115
	v_and_b32_e32 v23, 0xffff0000, v115
	v_add_f32_e32 v16, 1.0, v16
	v_add_f32_e32 v17, 1.0, v17
	v_add_f32_e32 v18, 1.0, v18
	v_add_f32_e32 v19, 1.0, v19
	v_rcp_f32_e32 v16, v16
	v_rcp_f32_e32 v17, v17
	v_rcp_f32_e32 v18, v18
	v_rcp_f32_e32 v19, v19
	v_sub_f32_e32 v20, v20, v227
	v_sub_f32_e32 v21, v21, v227
	v_sub_f32_e32 v22, v22, v227
	v_sub_f32_e32 v23, v23, v227
	v_mul_f32_e32 v20, v20, v228
	v_mul_f32_e32 v21, v21, v228
	v_mul_f32_e32 v22, v22, v228
	v_mul_f32_e32 v23, v23, v228
	v_mul_f32_e32 v12, v12, v16
	v_mul_f32_e32 v13, v13, v17
	v_mul_f32_e32 v14, v14, v18
	v_mul_f32_e32 v15, v15, v19
	v_mul_f32_e32 v20, v20, v96
	v_mul_f32_e32 v21, v21, v97
	v_mul_f32_e32 v22, v22, v98
	v_mul_f32_e32 v23, v23, v99
	v_mul_f32_e32 v20, v20, v12
	v_mul_f32_e32 v21, v21, v13
	v_mul_f32_e32 v22, v22, v14
	v_mul_f32_e32 v23, v23, v15
	v_cvt_pk_bf16_f32 v20, v20, v21
	v_cvt_pk_bf16_f32 v21, v22, v23
	global_store_dwordx2 v204, v[20:21], s[30:31] offset:736
	s_waitcnt vmcnt(29)
	v_lshlrev_b32_e32 v12, 16, v40
	v_and_b32_e32 v13, 0xffff0000, v40
	v_lshlrev_b32_e32 v14, 16, v41
	v_and_b32_e32 v15, 0xffff0000, v41
	v_mul_f32_e32 v16, 0xbfb8aa3b, v12
	v_mul_f32_e32 v17, 0xbfb8aa3b, v13
	v_mul_f32_e32 v18, 0xbfb8aa3b, v14
	v_mul_f32_e32 v19, 0xbfb8aa3b, v15
	v_exp_f32_e32 v16, v16
	v_exp_f32_e32 v17, v17
	v_exp_f32_e32 v18, v18
	v_exp_f32_e32 v19, v19
	v_lshlrev_b32_e32 v20, 16, v116
	v_and_b32_e32 v21, 0xffff0000, v116
	v_lshlrev_b32_e32 v22, 16, v117
	v_and_b32_e32 v23, 0xffff0000, v117
	v_add_f32_e32 v16, 1.0, v16
	v_add_f32_e32 v17, 1.0, v17
	v_add_f32_e32 v18, 1.0, v18
	v_add_f32_e32 v19, 1.0, v19
	v_rcp_f32_e32 v16, v16
	v_rcp_f32_e32 v17, v17
	v_rcp_f32_e32 v18, v18
	v_rcp_f32_e32 v19, v19
	v_sub_f32_e32 v20, v20, v227
	v_sub_f32_e32 v21, v21, v227
	v_sub_f32_e32 v22, v22, v227
	v_sub_f32_e32 v23, v23, v227
	v_mul_f32_e32 v20, v20, v228
	v_mul_f32_e32 v21, v21, v228
	v_mul_f32_e32 v22, v22, v228
	v_mul_f32_e32 v23, v23, v228
	v_mul_f32_e32 v12, v12, v16
	v_mul_f32_e32 v13, v13, v17
	v_mul_f32_e32 v14, v14, v18
	v_mul_f32_e32 v15, v15, v19
	v_mul_f32_e32 v20, v20, v132
	v_mul_f32_e32 v21, v21, v133
	v_mul_f32_e32 v22, v22, v134
	v_mul_f32_e32 v23, v23, v135
	v_mul_f32_e32 v20, v20, v12
	v_mul_f32_e32 v21, v21, v13
	v_mul_f32_e32 v22, v22, v14
	v_mul_f32_e32 v23, v23, v15
	v_cvt_pk_bf16_f32 v20, v20, v21
	v_cvt_pk_bf16_f32 v21, v22, v23
	global_store_dwordx2 v204, v[20:21], s[30:31] offset:768
	s_waitcnt vmcnt(27)
	v_lshlrev_b32_e32 v12, 16, v42
	v_and_b32_e32 v13, 0xffff0000, v42
	v_lshlrev_b32_e32 v14, 16, v43
	v_and_b32_e32 v15, 0xffff0000, v43
	v_mul_f32_e32 v16, 0xbfb8aa3b, v12
	v_mul_f32_e32 v17, 0xbfb8aa3b, v13
	v_mul_f32_e32 v18, 0xbfb8aa3b, v14
	v_mul_f32_e32 v19, 0xbfb8aa3b, v15
	v_exp_f32_e32 v16, v16
	v_exp_f32_e32 v17, v17
	v_exp_f32_e32 v18, v18
	v_exp_f32_e32 v19, v19
	v_lshlrev_b32_e32 v20, 16, v118
	v_and_b32_e32 v21, 0xffff0000, v118
	v_lshlrev_b32_e32 v22, 16, v119
	v_and_b32_e32 v23, 0xffff0000, v119
	v_add_f32_e32 v16, 1.0, v16
	v_add_f32_e32 v17, 1.0, v17
	v_add_f32_e32 v18, 1.0, v18
	v_add_f32_e32 v19, 1.0, v19
	v_rcp_f32_e32 v16, v16
	v_rcp_f32_e32 v17, v17
	v_rcp_f32_e32 v18, v18
	v_rcp_f32_e32 v19, v19
	v_sub_f32_e32 v20, v20, v227
	v_sub_f32_e32 v21, v21, v227
	v_sub_f32_e32 v22, v22, v227
	v_sub_f32_e32 v23, v23, v227
	v_mul_f32_e32 v20, v20, v228
	v_mul_f32_e32 v21, v21, v228
	v_mul_f32_e32 v22, v22, v228
	v_mul_f32_e32 v23, v23, v228
	v_mul_f32_e32 v12, v12, v16
	v_mul_f32_e32 v13, v13, v17
	v_mul_f32_e32 v14, v14, v18
	v_mul_f32_e32 v15, v15, v19
	v_mul_f32_e32 v20, v20, v136
	v_mul_f32_e32 v21, v21, v137
	v_mul_f32_e32 v22, v22, v138
	v_mul_f32_e32 v23, v23, v139
	v_mul_f32_e32 v20, v20, v12
	v_mul_f32_e32 v21, v21, v13
	v_mul_f32_e32 v22, v22, v14
	v_mul_f32_e32 v23, v23, v15
	v_cvt_pk_bf16_f32 v20, v20, v21
	v_cvt_pk_bf16_f32 v21, v22, v23
	global_store_dwordx2 v204, v[20:21], s[30:31] offset:800
	s_waitcnt vmcnt(25)
	v_lshlrev_b32_e32 v12, 16, v44
	v_and_b32_e32 v13, 0xffff0000, v44
	v_lshlrev_b32_e32 v14, 16, v45
	v_and_b32_e32 v15, 0xffff0000, v45
	v_mul_f32_e32 v16, 0xbfb8aa3b, v12
	v_mul_f32_e32 v17, 0xbfb8aa3b, v13
	v_mul_f32_e32 v18, 0xbfb8aa3b, v14
	v_mul_f32_e32 v19, 0xbfb8aa3b, v15
	v_exp_f32_e32 v16, v16
	v_exp_f32_e32 v17, v17
	v_exp_f32_e32 v18, v18
	v_exp_f32_e32 v19, v19
	v_lshlrev_b32_e32 v20, 16, v120
	v_and_b32_e32 v21, 0xffff0000, v120
	v_lshlrev_b32_e32 v22, 16, v121
	v_and_b32_e32 v23, 0xffff0000, v121
	v_add_f32_e32 v16, 1.0, v16
	v_add_f32_e32 v17, 1.0, v17
	v_add_f32_e32 v18, 1.0, v18
	v_add_f32_e32 v19, 1.0, v19
	v_rcp_f32_e32 v16, v16
	v_rcp_f32_e32 v17, v17
	v_rcp_f32_e32 v18, v18
	v_rcp_f32_e32 v19, v19
	v_sub_f32_e32 v20, v20, v227
	v_sub_f32_e32 v21, v21, v227
	v_sub_f32_e32 v22, v22, v227
	v_sub_f32_e32 v23, v23, v227
	v_mul_f32_e32 v20, v20, v228
	v_mul_f32_e32 v21, v21, v228
	v_mul_f32_e32 v22, v22, v228
	v_mul_f32_e32 v23, v23, v228
	v_mul_f32_e32 v12, v12, v16
	v_mul_f32_e32 v13, v13, v17
	v_mul_f32_e32 v14, v14, v18
	v_mul_f32_e32 v15, v15, v19
	v_mul_f32_e32 v20, v20, v144
	v_mul_f32_e32 v21, v21, v145
	v_mul_f32_e32 v22, v22, v146
	v_mul_f32_e32 v23, v23, v147
	v_mul_f32_e32 v20, v20, v12
	v_mul_f32_e32 v21, v21, v13
	v_mul_f32_e32 v22, v22, v14
	v_mul_f32_e32 v23, v23, v15
	v_cvt_pk_bf16_f32 v20, v20, v21
	v_cvt_pk_bf16_f32 v21, v22, v23
	global_store_dwordx2 v204, v[20:21], s[30:31] offset:832
	s_waitcnt vmcnt(23)
	v_lshlrev_b32_e32 v12, 16, v46
	v_and_b32_e32 v13, 0xffff0000, v46
	v_lshlrev_b32_e32 v14, 16, v47
	v_and_b32_e32 v15, 0xffff0000, v47
	v_mul_f32_e32 v16, 0xbfb8aa3b, v12
	v_mul_f32_e32 v17, 0xbfb8aa3b, v13
	v_mul_f32_e32 v18, 0xbfb8aa3b, v14
	v_mul_f32_e32 v19, 0xbfb8aa3b, v15
	v_exp_f32_e32 v16, v16
	v_exp_f32_e32 v17, v17
	v_exp_f32_e32 v18, v18
	v_exp_f32_e32 v19, v19
	v_lshlrev_b32_e32 v20, 16, v122
	v_and_b32_e32 v21, 0xffff0000, v122
	v_lshlrev_b32_e32 v22, 16, v123
	v_and_b32_e32 v23, 0xffff0000, v123
	v_add_f32_e32 v16, 1.0, v16
	v_add_f32_e32 v17, 1.0, v17
	v_add_f32_e32 v18, 1.0, v18
	v_add_f32_e32 v19, 1.0, v19
	v_rcp_f32_e32 v16, v16
	v_rcp_f32_e32 v17, v17
	v_rcp_f32_e32 v18, v18
	v_rcp_f32_e32 v19, v19
	v_sub_f32_e32 v20, v20, v227
	v_sub_f32_e32 v21, v21, v227
	v_sub_f32_e32 v22, v22, v227
	v_sub_f32_e32 v23, v23, v227
	v_mul_f32_e32 v20, v20, v228
	v_mul_f32_e32 v21, v21, v228
	v_mul_f32_e32 v22, v22, v228
	v_mul_f32_e32 v23, v23, v228
	v_mul_f32_e32 v12, v12, v16
	v_mul_f32_e32 v13, v13, v17
	v_mul_f32_e32 v14, v14, v18
	v_mul_f32_e32 v15, v15, v19
	v_mul_f32_e32 v20, v20, v148
	v_mul_f32_e32 v21, v21, v149
	v_mul_f32_e32 v22, v22, v150
	v_mul_f32_e32 v23, v23, v151
	v_mul_f32_e32 v20, v20, v12
	v_mul_f32_e32 v21, v21, v13
	v_mul_f32_e32 v22, v22, v14
	v_mul_f32_e32 v23, v23, v15
	v_cvt_pk_bf16_f32 v20, v20, v21
	v_cvt_pk_bf16_f32 v21, v22, v23
	global_store_dwordx2 v204, v[20:21], s[30:31] offset:864
	s_waitcnt vmcnt(21)
	v_lshlrev_b32_e32 v12, 16, v48
	v_and_b32_e32 v13, 0xffff0000, v48
	v_lshlrev_b32_e32 v14, 16, v49
	v_and_b32_e32 v15, 0xffff0000, v49
	v_mul_f32_e32 v16, 0xbfb8aa3b, v12
	v_mul_f32_e32 v17, 0xbfb8aa3b, v13
	v_mul_f32_e32 v18, 0xbfb8aa3b, v14
	v_mul_f32_e32 v19, 0xbfb8aa3b, v15
	v_exp_f32_e32 v16, v16
	v_exp_f32_e32 v17, v17
	v_exp_f32_e32 v18, v18
	v_exp_f32_e32 v19, v19
	v_lshlrev_b32_e32 v20, 16, v124
	v_and_b32_e32 v21, 0xffff0000, v124
	v_lshlrev_b32_e32 v22, 16, v125
	v_and_b32_e32 v23, 0xffff0000, v125
	v_add_f32_e32 v16, 1.0, v16
	v_add_f32_e32 v17, 1.0, v17
	v_add_f32_e32 v18, 1.0, v18
	v_add_f32_e32 v19, 1.0, v19
	v_rcp_f32_e32 v16, v16
	v_rcp_f32_e32 v17, v17
	v_rcp_f32_e32 v18, v18
	v_rcp_f32_e32 v19, v19
	v_sub_f32_e32 v20, v20, v227
	v_sub_f32_e32 v21, v21, v227
	v_sub_f32_e32 v22, v22, v227
	v_sub_f32_e32 v23, v23, v227
	v_mul_f32_e32 v20, v20, v228
	v_mul_f32_e32 v21, v21, v228
	v_mul_f32_e32 v22, v22, v228
	v_mul_f32_e32 v23, v23, v228
	v_mul_f32_e32 v12, v12, v16
	v_mul_f32_e32 v13, v13, v17
	v_mul_f32_e32 v14, v14, v18
	v_mul_f32_e32 v15, v15, v19
	v_mul_f32_e32 v20, v20, v152
	v_mul_f32_e32 v21, v21, v153
	v_mul_f32_e32 v22, v22, v154
	v_mul_f32_e32 v23, v23, v155
	v_mul_f32_e32 v20, v20, v12
	v_mul_f32_e32 v21, v21, v13
	v_mul_f32_e32 v22, v22, v14
	v_mul_f32_e32 v23, v23, v15
	v_cvt_pk_bf16_f32 v20, v20, v21
	v_cvt_pk_bf16_f32 v21, v22, v23
	global_store_dwordx2 v204, v[20:21], s[30:31] offset:896
	s_waitcnt vmcnt(19)
	v_lshlrev_b32_e32 v12, 16, v50
	v_and_b32_e32 v13, 0xffff0000, v50
	v_lshlrev_b32_e32 v14, 16, v51
	v_and_b32_e32 v15, 0xffff0000, v51
	v_mul_f32_e32 v16, 0xbfb8aa3b, v12
	v_mul_f32_e32 v17, 0xbfb8aa3b, v13
	v_mul_f32_e32 v18, 0xbfb8aa3b, v14
	v_mul_f32_e32 v19, 0xbfb8aa3b, v15
	v_exp_f32_e32 v16, v16
	v_exp_f32_e32 v17, v17
	v_exp_f32_e32 v18, v18
	v_exp_f32_e32 v19, v19
	v_lshlrev_b32_e32 v20, 16, v126
	v_and_b32_e32 v21, 0xffff0000, v126
	v_lshlrev_b32_e32 v22, 16, v127
	v_and_b32_e32 v23, 0xffff0000, v127
	v_add_f32_e32 v16, 1.0, v16
	v_add_f32_e32 v17, 1.0, v17
	v_add_f32_e32 v18, 1.0, v18
	v_add_f32_e32 v19, 1.0, v19
	v_rcp_f32_e32 v16, v16
	v_rcp_f32_e32 v17, v17
	v_rcp_f32_e32 v18, v18
	v_rcp_f32_e32 v19, v19
	v_sub_f32_e32 v20, v20, v227
	v_sub_f32_e32 v21, v21, v227
	v_sub_f32_e32 v22, v22, v227
	v_sub_f32_e32 v23, v23, v227
	v_mul_f32_e32 v20, v20, v228
	v_mul_f32_e32 v21, v21, v228
	v_mul_f32_e32 v22, v22, v228
	v_mul_f32_e32 v23, v23, v228
	v_mul_f32_e32 v12, v12, v16
	v_mul_f32_e32 v13, v13, v17
	v_mul_f32_e32 v14, v14, v18
	v_mul_f32_e32 v15, v15, v19
	v_mul_f32_e32 v20, v20, v156
	v_mul_f32_e32 v21, v21, v157
	v_mul_f32_e32 v22, v22, v158
	v_mul_f32_e32 v23, v23, v159
	v_mul_f32_e32 v20, v20, v12
	v_mul_f32_e32 v21, v21, v13
	v_mul_f32_e32 v22, v22, v14
	v_mul_f32_e32 v23, v23, v15
	v_cvt_pk_bf16_f32 v20, v20, v21
	v_cvt_pk_bf16_f32 v21, v22, v23
	global_store_dwordx2 v204, v[20:21], s[30:31] offset:928
	s_waitcnt vmcnt(17)
	v_lshlrev_b32_e32 v12, 16, v52
	v_and_b32_e32 v13, 0xffff0000, v52
	v_lshlrev_b32_e32 v14, 16, v53
	v_and_b32_e32 v15, 0xffff0000, v53
	v_mul_f32_e32 v16, 0xbfb8aa3b, v12
	v_mul_f32_e32 v17, 0xbfb8aa3b, v13
	v_mul_f32_e32 v18, 0xbfb8aa3b, v14
	v_mul_f32_e32 v19, 0xbfb8aa3b, v15
	v_exp_f32_e32 v16, v16
	v_exp_f32_e32 v17, v17
	v_exp_f32_e32 v18, v18
	v_exp_f32_e32 v19, v19
	v_lshlrev_b32_e32 v20, 16, v128
	v_and_b32_e32 v21, 0xffff0000, v128
	v_lshlrev_b32_e32 v22, 16, v129
	v_and_b32_e32 v23, 0xffff0000, v129
	v_add_f32_e32 v16, 1.0, v16
	v_add_f32_e32 v17, 1.0, v17
	v_add_f32_e32 v18, 1.0, v18
	v_add_f32_e32 v19, 1.0, v19
	v_rcp_f32_e32 v16, v16
	v_rcp_f32_e32 v17, v17
	v_rcp_f32_e32 v18, v18
	v_rcp_f32_e32 v19, v19
	v_sub_f32_e32 v20, v20, v227
	v_sub_f32_e32 v21, v21, v227
	v_sub_f32_e32 v22, v22, v227
	v_sub_f32_e32 v23, v23, v227
	v_mul_f32_e32 v20, v20, v228
	v_mul_f32_e32 v21, v21, v228
	v_mul_f32_e32 v22, v22, v228
	v_mul_f32_e32 v23, v23, v228
	v_mul_f32_e32 v12, v12, v16
	v_mul_f32_e32 v13, v13, v17
	v_mul_f32_e32 v14, v14, v18
	v_mul_f32_e32 v15, v15, v19
	v_mul_f32_e32 v20, v20, v160
	v_mul_f32_e32 v21, v21, v161
	v_mul_f32_e32 v22, v22, v162
	v_mul_f32_e32 v23, v23, v163
	v_mul_f32_e32 v20, v20, v12
	v_mul_f32_e32 v21, v21, v13
	v_mul_f32_e32 v22, v22, v14
	v_mul_f32_e32 v23, v23, v15
	v_cvt_pk_bf16_f32 v20, v20, v21
	v_cvt_pk_bf16_f32 v21, v22, v23
	global_store_dwordx2 v204, v[20:21], s[30:31] offset:960
	s_waitcnt vmcnt(15)
	v_lshlrev_b32_e32 v12, 16, v54
	v_and_b32_e32 v13, 0xffff0000, v54
	v_lshlrev_b32_e32 v14, 16, v55
	v_and_b32_e32 v15, 0xffff0000, v55
	v_mul_f32_e32 v16, 0xbfb8aa3b, v12
	v_mul_f32_e32 v17, 0xbfb8aa3b, v13
	v_mul_f32_e32 v18, 0xbfb8aa3b, v14
	v_mul_f32_e32 v19, 0xbfb8aa3b, v15
	v_exp_f32_e32 v16, v16
	v_exp_f32_e32 v17, v17
	v_exp_f32_e32 v18, v18
	v_exp_f32_e32 v19, v19
	v_lshlrev_b32_e32 v20, 16, v130
	v_and_b32_e32 v21, 0xffff0000, v130
	v_lshlrev_b32_e32 v22, 16, v131
	v_and_b32_e32 v23, 0xffff0000, v131
	v_add_f32_e32 v16, 1.0, v16
	v_add_f32_e32 v17, 1.0, v17
	v_add_f32_e32 v18, 1.0, v18
	v_add_f32_e32 v19, 1.0, v19
	v_rcp_f32_e32 v16, v16
	v_rcp_f32_e32 v17, v17
	v_rcp_f32_e32 v18, v18
	v_rcp_f32_e32 v19, v19
	v_sub_f32_e32 v20, v20, v227
	v_sub_f32_e32 v21, v21, v227
	v_sub_f32_e32 v22, v22, v227
	v_sub_f32_e32 v23, v23, v227
	v_mul_f32_e32 v20, v20, v228
	v_mul_f32_e32 v21, v21, v228
	v_mul_f32_e32 v22, v22, v228
	v_mul_f32_e32 v23, v23, v228
	v_mul_f32_e32 v12, v12, v16
	v_mul_f32_e32 v13, v13, v17
	v_mul_f32_e32 v14, v14, v18
	v_mul_f32_e32 v15, v15, v19
	v_mul_f32_e32 v20, v20, v164
	v_mul_f32_e32 v21, v21, v165
	v_mul_f32_e32 v22, v22, v166
	v_mul_f32_e32 v23, v23, v167
	v_mul_f32_e32 v20, v20, v12
	v_mul_f32_e32 v21, v21, v13
	v_mul_f32_e32 v22, v22, v14
	v_mul_f32_e32 v23, v23, v15
	v_cvt_pk_bf16_f32 v20, v20, v21
	v_cvt_pk_bf16_f32 v21, v22, v23
	global_store_dwordx2 v204, v[20:21], s[30:31] offset:992
	s_waitcnt vmcnt(0)
	s_add_i32 s6, s6, 1
	s_cmp_lt_i32 s6, 2
	s_cbranch_scc1 .Lintra_unit
	s_setprio 0
	s_branch .LBB0_748

.LBB0_1161:
	s_andn2_b64 vcc, exec, s[0:1]
	s_cbranch_vccnz .LBB0_1273
	v_readlane_b32 s2, v254, 5
	v_readlane_b32 s3, v254, 6
	v_mov_b32_e32 v0, v208
	v_readlane_b32 s5, v254, 0
	s_load_dwordx4 s[40:43], s[2:3], 0xa0
	s_load_dword s4, s[2:3], 0xb0
	s_and_b32 s6, s5, -8
	v_ashrrev_i32_e32 v1, 6, v0
	v_mul_lo_u32 v2, v1, s46
	v_add_u32_e32 v1, s6, v1
	v_readlane_b32 s6, v254, 14
	v_add_u32_e32 v2, s5, v2
	v_readlane_b32 s7, v254, 15
	s_waitcnt lgkmcnt(0)
	s_mov_b64 s[0:1], s[42:43]
	v_cndmask_b32_e64 v49, v2, v1, s[6:7]
	v_readlane_b32 s6, v254, 16
	s_nop 1
	v_cmp_gt_i32_e32 vcc, s6, v49
	s_and_saveexec_b64 s[30:31], vcc
	s_cbranch_execz .LBB0_1215
	s_cmpk_lg_i32 s46, 0x100
	s_cbranch_scc1 .Lband_orig
	s_load_dwordx2 s[6:7], s[2:3], 0x30
	v_readlane_b32 s8, v254, 33
	s_and_b32 s56, s5, 7
	s_lshl_b32 s8, s8, 3
	s_add_i32 s8, s8, s56
	s_lshl_b32 s8, s8, 2
	s_waitcnt lgkmcnt(0)
	s_load_dword s9, s[6:7], s8
	v_lshrrev_b32_e32 v0, 6, v208
	s_waitcnt lgkmcnt(0)
	v_readfirstlane_b32 s1, v0
	s_cmp_lt_u32 s1, 4
	s_cbranch_scc1 .Lb_prio_done
	s_setprio 1
.Lb_prio_done:
	s_lshr_b32 s7, s5, 3
	s_lshl_b32 s7, s7, 3
	s_add_i32 s7, s7, s1
	s_lshl_b32 s48, s1, 10
	s_mov_b32 s40, 0x3e38aa3b
	s_mov_b32 s41, 0x3e38aa3b
	s_mov_b32 s57, 0x20400
	s_mul_i32 s0, s1, 0x1200
	s_add_i32 s0, s0, 0x2000
	v_and_b32_e32 v100, 63, v208
	v_lshrrev_b32_e32 v101, 3, v100
	v_mul_u32_u24_e32 v101, 0x90, v101
	v_and_b32_e32 v102, 7, v100
	v_lshl_add_u32 v101, v102, 4, v101
	v_add_u32_e32 v114, s0, v101
	v_bfe_u32 v101, v208, 4, 2
	v_mul_u32_u24_e32 v101, 0x240, v101
	v_and_b32_e32 v102, 15, v208
	v_lshl_add_u32 v101, v102, 1, v101
	v_add_u32_e32 v115, s0, v101
	v_and_b32_e32 v116, 15, v208
	v_bfe_u32 v100, v208, 4, 2
	v_lshlrev_b32_e32 v117, 2, v100
	v_lshlrev_b32_e32 v118, 3, v100
	v_cmp_eq_u32_e32 vcc, 0, v100
	s_nop 1
	v_cndmask_b32_e64 v120, 0, 1.0, vcc
	s_waitcnt lgkmcnt(0)
	v_mov_b32_e32 v119, s9
	v_mul_f32_e32 v119, 0x3fb8aa3b, v119
	s_mov_b32 s6, 0
	s_lshr_b32 s0, s6, 2
	s_cmp_eq_u32 s0, 0
	s_cselect_b32 s3, 1, 0
	s_add_i32 s1, s0, -1
	s_max_i32 s1, s1, 0
	s_lshl_b32 s13, s1, 1
	s_and_b32 s1, s6, 1
	s_lshl_b32 s1, s1, 8
	s_add_i32 s1, s1, s7
	s_lshl_b32 s1, s1, 1
	s_sub_i32 s2, 10, s13
	s_lshr_b32 s14, s1, s2
	s_lshr_b32 s2, 0x400, s13
	s_add_i32 s2, s2, -1
	s_and_b32 s1, s1, s2
	s_lshl_b32 s8, s1, 4
	s_add_i32 s22, s1, 1
	s_sub_i32 s2, 0x80, s3
	s_sub_i32 s2, s8, s2
	s_max_i32 s2, s2, 0
	s_lshr_b32 s2, s2, 4
	s_and_b32 s15, s2, -2
	s_sub_i32 s2, s22, s15
	s_lshr_b32 s2, s2, 1
	s_add_i32 s9, s2, 1
	s_bfe_u32 s2, s6, 0x10001
	s_mul_i32 s2, s2, 0x4800000
	s_mul_i32 s0, s14, 0x1200
	s_add_i32 s2, s2, s0
	s_add_i32 s2, s2, 0xcd00000
	s_add_u32 s86, s42, s2
	s_addc_u32 s87, s43, 0
	s_lshl_b32 s0, 0x12000, s13
	s_mul_i32 s39, s1, s0
	s_lshl_b32 s1, s56, 7
	s_mul_i32 s2, s3, 0x600
	s_sub_i32 s2, 0x600, s2
	s_add_i32 s2, s2, s1
	s_add_i32 s2, s2, s39
	s_add_u32 s62, s86, s2
	s_addc_u32 s63, s87, 0
	s_mov_b32 s10, 0
	v_lshlrev_b32_e32 v90, s13, v116
	v_mul_u32_u24_e32 v90, 0x1200, v90
	v_lshl_add_u32 v204, v118, 1, v90
	global_load_dwordx4 v[16:19], v204, s[62:63]
	global_load_dwordx4 v[20:23], v204, s[62:63] offset:64
	s_lshl_b32 s0, 0x12000, s13
	s_add_u32 s62, s62, s0
	s_addc_u32 s63, s63, 0
	global_load_dwordx4 v[160:163], v204, s[62:63]
	global_load_dwordx4 v[164:167], v204, s[62:63] offset:64
	s_mov_b32 s11, 0
	s_lshr_b32 s0, s11, 2
	s_cmp_eq_u32 s0, 0
	s_cselect_b32 s3, 1, 0
	s_add_i32 s1, s0, -1
	s_max_i32 s1, s1, 0
	s_lshl_b32 s37, s1, 1
	s_and_b32 s1, s11, 1
	s_lshl_b32 s1, s1, 8
	s_add_i32 s1, s1, s7
	s_lshl_b32 s1, s1, 1
	s_sub_i32 s2, 10, s37
	s_lshr_b32 s16, s1, s2
	s_lshr_b32 s2, 0x400, s37
	s_add_i32 s2, s2, -1
	s_and_b32 s1, s1, s2
	s_lshl_b32 s20, s1, 4
	s_add_i32 s36, s1, 1
	s_sub_i32 s2, 0x80, s3
	s_sub_i32 s2, s20, s2
	s_max_i32 s2, s2, 0
	s_lshr_b32 s2, s2, 4
	s_and_b32 s12, s2, -2
	s_sub_i32 s2, s36, s12
	s_lshr_b32 s2, s2, 1
	s_add_i32 s35, s2, 1
	s_bfe_u32 s2, s11, 0x10001
	s_mul_i32 s2, s2, 0x4800000
	s_mul_i32 s0, s16, 0x1200
	s_add_i32 s2, s2, s0
	s_add_i32 s2, s2, 0xcd00000
	s_add_u32 s86, s42, s2
	s_addc_u32 s87, s43, 0
	s_lshl_b32 s0, 0x12000, s37
	s_mul_i32 s39, s1, s0
	s_lshl_b32 s1, s56, 7
	s_lshr_b32 s2, s56, 2
	s_lshl_b32 s2, s2, 7
	s_cmp_eq_u32 s3, 1
	s_cselect_b32 s0, s2, s1
	s_mul_i32 s2, s3, 0x600
	s_sub_i32 s2, 0xa00, s2
	s_add_i32 s2, s2, s0
	s_add_u32 s24, s86, s2
	s_addc_u32 s25, s87, 0
	s_mul_i32 s2, s3, 0x900
	s_sub_i32 s2, 0xe00, s2
	s_add_i32 s2, s2, s0
	s_add_u32 s26, s86, s2
	s_addc_u32 s27, s87, 0
	v_lshlrev_b32_e32 v90, s37, v116
	v_mul_u32_u24_e32 v90, 0x1200, v90
	v_lshl_add_u32 v111, v118, 1, v90
	v_and_b32_e32 v90, 63, v208
	v_and_b32_e32 v123, 7, v90
	v_lshlrev_b32_e32 v123, 4, v123
	v_lshrrev_b32_e32 v90, 3, v90
	v_add_u32_e32 v91, 0, v90
	v_lshlrev_b32_e32 v91, s37, v91
	v_mul_u32_u24_e32 v91, 0x1200, v91
	v_add_u32_e32 v112, v91, v123
	v_add_u32_e32 v91, 8, v90
	v_lshlrev_b32_e32 v91, s37, v91
	v_mul_u32_u24_e32 v91, 0x1200, v91
	v_add_u32_e32 v113, v91, v123
	s_mov_b32 s34, 0
	s_lshl_b32 s1, 0x12000, s37
	s_mul_i32 s0, s12, s1
	s_add_u32 s16, s24, s0
	s_addc_u32 s17, s25, 0
	s_add_u32 s20, s26, s0
	s_addc_u32 s21, s27, 0
	s_add_i32 s2, s12, 1
	s_cmp_gt_i32 s2, s36
	s_cselect_b32 s2, s12, s2
	s_mul_i32 s0, s2, s1
	s_add_u32 s18, s24, s0
	s_addc_u32 s19, s25, 0
	s_add_u32 s22, s26, s0
	s_addc_u32 s23, s27, 0
	global_load_dwordx4 v[24:27], v111, s[16:17]
	global_load_dwordx4 v[28:31], v111, s[16:17] offset:64
	global_load_dwordx4 v[32:35], v111, s[18:19]
	global_load_dwordx4 v[36:39], v111, s[18:19] offset:64
	global_load_dwordx4 v[40:43], v112, s[20:21]
	global_load_dwordx4 v[44:47], v113, s[20:21]
	global_load_dwordx4 v[48:51], v112, s[22:23]
	global_load_dwordx4 v[52:55], v113, s[22:23]
	s_add_i32 s0, s34, 1
	s_cmp_lt_i32 s0, s35
	s_cbranch_scc1 .Lb_pfsamee
	s_cmp_ge_i32 s11, 15
	s_cbranch_scc1 .Lb_pfgoe
	s_add_i32 s11, s11, 1
	s_lshr_b32 s0, s11, 2
	s_cmp_eq_u32 s0, 0
	s_cselect_b32 s3, 1, 0
	s_add_i32 s1, s0, -1
	s_max_i32 s1, s1, 0
	s_lshl_b32 s37, s1, 1
	s_and_b32 s1, s11, 1
	s_lshl_b32 s1, s1, 8
	s_add_i32 s1, s1, s7
	s_lshl_b32 s1, s1, 1
	s_sub_i32 s2, 10, s37
	s_lshr_b32 s16, s1, s2
	s_lshr_b32 s2, 0x400, s37
	s_add_i32 s2, s2, -1
	s_and_b32 s1, s1, s2
	s_lshl_b32 s20, s1, 4
	s_add_i32 s36, s1, 1
	s_sub_i32 s2, 0x80, s3
	s_sub_i32 s2, s20, s2
	s_max_i32 s2, s2, 0
	s_lshr_b32 s2, s2, 4
	s_and_b32 s12, s2, -2
	s_sub_i32 s2, s36, s12
	s_lshr_b32 s2, s2, 1
	s_add_i32 s35, s2, 1
	s_bfe_u32 s2, s11, 0x10001
	s_mul_i32 s2, s2, 0x4800000
	s_mul_i32 s0, s16, 0x1200
	s_add_i32 s2, s2, s0
	s_add_i32 s2, s2, 0xcd00000
	s_add_u32 s86, s42, s2
	s_addc_u32 s87, s43, 0
	s_lshl_b32 s0, 0x12000, s37
	s_mul_i32 s39, s1, s0
	s_lshl_b32 s1, s56, 7
	s_lshr_b32 s2, s56, 2
	s_lshl_b32 s2, s2, 7
	s_cmp_eq_u32 s3, 1
	s_cselect_b32 s0, s2, s1
	s_mul_i32 s2, s3, 0x600
	s_sub_i32 s2, 0xa00, s2
	s_add_i32 s2, s2, s0
	s_add_u32 s24, s86, s2
	s_addc_u32 s25, s87, 0
	s_mul_i32 s2, s3, 0x900
	s_sub_i32 s2, 0xe00, s2
	s_add_i32 s2, s2, s0
	s_add_u32 s26, s86, s2
	s_addc_u32 s27, s87, 0
	v_lshlrev_b32_e32 v90, s37, v116
	v_mul_u32_u24_e32 v90, 0x1200, v90
	v_lshl_add_u32 v111, v118, 1, v90
	v_and_b32_e32 v90, 63, v208
	v_and_b32_e32 v123, 7, v90
	v_lshlrev_b32_e32 v123, 4, v123
	v_lshrrev_b32_e32 v90, 3, v90
	v_add_u32_e32 v91, 0, v90
	v_lshlrev_b32_e32 v91, s37, v91
	v_mul_u32_u24_e32 v91, 0x1200, v91
	v_add_u32_e32 v112, v91, v123
	v_add_u32_e32 v91, 8, v90
	v_lshlrev_b32_e32 v91, s37, v91
	v_mul_u32_u24_e32 v91, 0x1200, v91
	v_add_u32_e32 v113, v91, v123
	s_mov_b32 s34, 0
	s_branch .Lb_pfgoe
